# G6 + s_setprio 1 during the LOAD segments (ds_read / LDS-DMA issue), 0 during MFMA segments
# speedup vs baseline: 1.0051x; 1.0051x over previous
.LBB0_200:
	ds_read_b128 v[148:151], v169
	ds_read_b128 v[152:155], v169 offset:1024
	ds_read_b128 v[156:159], v169 offset:2048
	ds_read_b128 v[160:163], v169 offset:3072
	ds_read_b128 v[174:177], v170
	ds_read_b128 v[178:181], v170 offset:1024
	ds_read_b128 v[182:185], v170 offset:2048
	ds_read_b128 v[186:189], v170 offset:3072
	s_add_u32 s26, s6, 0xfff00800
	s_addc_u32 s27, s7, -1
	s_cmp_eq_u32 s34, 60
	s_cselect_b32 s29, s17, s27
	s_cselect_b32 s28, s23, s26
	s_cselect_b32 s27, s15, s31
	s_cselect_b32 s26, s25, s30
	v_lshl_add_u64 v[190:191], s[6:7], 0, v[138:139]
	s_add_i32 m0, s41, 0xc000
	s_nop 0
	global_load_lds_dwordx4 v[190:191], off
	v_lshl_add_u64 v[190:191], s[6:7], 0, v[140:141]
	s_add_i32 m0, s41, 0xe000
	s_nop 0
	global_load_lds_dwordx4 v[190:191], off
	ds_read_b128 v[190:193], v171
	ds_read_b128 v[194:197], v171 offset:1024
	ds_read_b128 v[198:201], v171 offset:2048
	ds_read_b128 v[202:205], v171 offset:3072
	ds_read_b128 v[206:209], v171 offset:4096
	ds_read_b128 v[210:213], v171 offset:5120
	ds_read_b128 v[214:217], v171 offset:6144
	ds_read_b128 v[218:221], v171 offset:7168
	s_setprio 0
	s_waitcnt vmcnt(8)
	s_waitcnt lgkmcnt(0)
	s_barrier
	s_waitcnt lgkmcnt(0)
	v_mfma_f32_16x16x32_bf16 v[124:127], v[148:151], v[190:193], v[124:127]
	v_mfma_f32_16x16x32_bf16 v[124:127], v[152:155], v[194:197], v[124:127]
	v_mfma_f32_16x16x32_bf16 v[120:123], v[160:163], v[194:197], v[120:123]
	v_mfma_f32_16x16x32_bf16 v[120:123], v[156:159], v[190:193], v[120:123]
	v_mfma_f32_16x16x32_bf16 v[60:63], v[174:177], v[190:193], v[60:63]
	v_mfma_f32_16x16x32_bf16 v[60:63], v[178:181], v[194:197], v[60:63]
	v_mfma_f32_16x16x32_bf16 v[56:59], v[186:189], v[194:197], v[56:59]
	v_mfma_f32_16x16x32_bf16 v[56:59], v[182:185], v[190:193], v[56:59]
	v_mfma_f32_16x16x32_bf16 v[48:51], v[182:185], v[198:201], v[48:51]
	v_mfma_f32_16x16x32_bf16 v[48:51], v[186:189], v[202:205], v[48:51]
	v_mfma_f32_16x16x32_bf16 v[52:55], v[178:181], v[202:205], v[52:55]
	v_mfma_f32_16x16x32_bf16 v[52:55], v[174:177], v[198:201], v[52:55]
	v_mfma_f32_16x16x32_bf16 v[112:115], v[156:159], v[198:201], v[112:115]
	v_mfma_f32_16x16x32_bf16 v[112:115], v[160:163], v[202:205], v[112:115]
	v_mfma_f32_16x16x32_bf16 v[116:119], v[152:155], v[202:205], v[116:119]
	v_mfma_f32_16x16x32_bf16 v[116:119], v[148:151], v[198:201], v[116:119]
	v_mfma_f32_16x16x32_bf16 v[108:111], v[148:151], v[206:209], v[108:111]
	v_mfma_f32_16x16x32_bf16 v[108:111], v[152:155], v[210:213], v[108:111]
	v_mfma_f32_16x16x32_bf16 v[104:107], v[160:163], v[210:213], v[104:107]
	v_mfma_f32_16x16x32_bf16 v[104:107], v[156:159], v[206:209], v[104:107]
	v_mfma_f32_16x16x32_bf16 v[44:47], v[174:177], v[206:209], v[44:47]
	v_mfma_f32_16x16x32_bf16 v[44:47], v[178:181], v[210:213], v[44:47]
	v_mfma_f32_16x16x32_bf16 v[40:43], v[186:189], v[210:213], v[40:43]
	v_mfma_f32_16x16x32_bf16 v[40:43], v[182:185], v[206:209], v[40:43]
	v_mfma_f32_16x16x32_bf16 v[32:35], v[182:185], v[214:217], v[32:35]
	v_mfma_f32_16x16x32_bf16 v[32:35], v[186:189], v[218:221], v[32:35]
	v_mfma_f32_16x16x32_bf16 v[36:39], v[178:181], v[218:221], v[36:39]
	v_mfma_f32_16x16x32_bf16 v[36:39], v[174:177], v[214:217], v[36:39]
	v_mfma_f32_16x16x32_bf16 v[96:99], v[156:159], v[214:217], v[96:99]
	v_mfma_f32_16x16x32_bf16 v[96:99], v[160:163], v[218:221], v[96:99]
	v_mfma_f32_16x16x32_bf16 v[100:103], v[152:155], v[218:221], v[100:103]
	v_mfma_f32_16x16x32_bf16 v[100:103], v[148:151], v[214:217], v[100:103]
	s_barrier
	s_setprio 1
	s_add_i32 s35, s55, s36
	v_lshl_add_u64 v[222:223], s[26:27], 0, v[130:131]
	s_mov_b32 m0, s35
	v_lshl_add_u64 v[224:225], s[26:27], 0, v[134:135]
	global_load_lds_dwordx4 v[222:223], off
	s_add_i32 m0, s35, 0x2000
	s_add_u32 s58, s26, 0x100000
	s_addc_u32 s59, s27, 0
	s_add_i32 s35, s56, s36
	global_load_lds_dwordx4 v[224:225], off
	v_lshl_add_u64 v[190:191], s[58:59], 0, v[130:131]
	s_mov_b32 m0, s35
	v_lshl_add_u64 v[226:227], s[28:29], 0, v[128:129]
	global_load_lds_dwordx4 v[190:191], off
	v_lshl_add_u64 v[190:191], s[58:59], 0, v[134:135]
	s_add_i32 m0, s35, 0x2000
	v_lshl_add_u64 v[228:229], s[28:29], 0, v[132:133]
	global_load_lds_dwordx4 v[190:191], off
	s_mov_b32 m0, s41
	s_nop 0
	global_load_lds_dwordx4 v[226:227], off
	s_mov_b32 m0, s42
	s_nop 0
	global_load_lds_dwordx4 v[228:229], off
	ds_read_b128 v[190:193], v171 offset:16384
	ds_read_b128 v[194:197], v171 offset:17408
	ds_read_b128 v[198:201], v171 offset:18432
	ds_read_b128 v[202:205], v171 offset:19456
	ds_read_b128 v[206:209], v171 offset:20480
	ds_read_b128 v[210:213], v171 offset:21504
	ds_read_b128 v[214:217], v171 offset:22528
	ds_read_b128 v[218:221], v171 offset:23552
	s_setprio 0
	s_waitcnt vmcnt(8)
	s_waitcnt lgkmcnt(0)
	s_barrier
	s_waitcnt lgkmcnt(0)
	v_mfma_f32_16x16x32_bf16 v[92:95], v[148:151], v[190:193], v[92:95]
	v_mfma_f32_16x16x32_bf16 v[92:95], v[152:155], v[194:197], v[92:95]
	v_mfma_f32_16x16x32_bf16 v[88:91], v[160:163], v[194:197], v[88:91]
	v_mfma_f32_16x16x32_bf16 v[88:91], v[156:159], v[190:193], v[88:91]
	v_mfma_f32_16x16x32_bf16 v[28:31], v[174:177], v[190:193], v[28:31]
	v_mfma_f32_16x16x32_bf16 v[28:31], v[178:181], v[194:197], v[28:31]
	v_mfma_f32_16x16x32_bf16 v[24:27], v[186:189], v[194:197], v[24:27]
	v_mfma_f32_16x16x32_bf16 v[24:27], v[182:185], v[190:193], v[24:27]
	v_mfma_f32_16x16x32_bf16 v[16:19], v[182:185], v[198:201], v[16:19]
	v_mfma_f32_16x16x32_bf16 v[16:19], v[186:189], v[202:205], v[16:19]
	v_mfma_f32_16x16x32_bf16 v[20:23], v[178:181], v[202:205], v[20:23]
	v_mfma_f32_16x16x32_bf16 v[20:23], v[174:177], v[198:201], v[20:23]
	v_mfma_f32_16x16x32_bf16 v[80:83], v[156:159], v[198:201], v[80:83]
	v_mfma_f32_16x16x32_bf16 v[80:83], v[160:163], v[202:205], v[80:83]
	v_mfma_f32_16x16x32_bf16 v[84:87], v[152:155], v[202:205], v[84:87]
	v_mfma_f32_16x16x32_bf16 v[84:87], v[148:151], v[198:201], v[84:87]
	v_mfma_f32_16x16x32_bf16 v[76:79], v[148:151], v[206:209], v[76:79]
	v_mfma_f32_16x16x32_bf16 v[76:79], v[152:155], v[210:213], v[76:79]
	v_mfma_f32_16x16x32_bf16 v[72:75], v[160:163], v[210:213], v[72:75]
	v_mfma_f32_16x16x32_bf16 v[72:75], v[156:159], v[206:209], v[72:75]
	v_mfma_f32_16x16x32_bf16 v[12:15], v[174:177], v[206:209], v[12:15]
	v_mfma_f32_16x16x32_bf16 v[12:15], v[178:181], v[210:213], v[12:15]
	v_mfma_f32_16x16x32_bf16 v[8:11], v[186:189], v[210:213], v[8:11]
	v_mfma_f32_16x16x32_bf16 v[8:11], v[182:185], v[206:209], v[8:11]
	v_mfma_f32_16x16x32_bf16 v[0:3], v[182:185], v[214:217], v[0:3]
	v_mfma_f32_16x16x32_bf16 v[0:3], v[186:189], v[218:221], v[0:3]
	v_mfma_f32_16x16x32_bf16 v[4:7], v[178:181], v[218:221], v[4:7]
	v_mfma_f32_16x16x32_bf16 v[4:7], v[174:177], v[214:217], v[4:7]
	v_mfma_f32_16x16x32_bf16 v[64:67], v[156:159], v[214:217], v[64:67]
	v_mfma_f32_16x16x32_bf16 v[64:67], v[160:163], v[218:221], v[64:67]
	v_mfma_f32_16x16x32_bf16 v[68:71], v[152:155], v[218:221], v[68:71]
	v_mfma_f32_16x16x32_bf16 v[68:71], v[148:151], v[214:217], v[68:71]
	s_barrier
	s_setprio 1
	s_add_i32 s35, 0, 0x18000
	v_add_u32_e32 v136, s35, v165
	s_add_i32 s57, 0, 0x1c000
	ds_read_b128 v[148:151], v136
	ds_read_b128 v[152:155], v136 offset:1024
	ds_read_b128 v[156:159], v136 offset:2048
	ds_read_b128 v[160:163], v136 offset:3072
	v_add_u32_e32 v136, s57, v165
	ds_read_b128 v[174:177], v136
	ds_read_b128 v[178:181], v136 offset:1024
	ds_read_b128 v[182:185], v136 offset:2048
	ds_read_b128 v[186:189], v136 offset:3072
	s_add_u32 s28, s28, 0x100000
	s_addc_u32 s29, s29, 0
	s_mov_b32 m0, s43
	v_lshl_add_u64 v[190:191], s[28:29], 0, v[128:129]
	global_load_lds_dwordx4 v[190:191], off
	v_lshl_add_u64 v[190:191], s[28:29], 0, v[132:133]
	s_mov_b32 m0, s44
	s_nop 0
	global_load_lds_dwordx4 v[190:191], off
	ds_read_b128 v[190:193], v171 offset:32768
	ds_read_b128 v[194:197], v171 offset:33792
	ds_read_b128 v[198:201], v171 offset:34816
	ds_read_b128 v[202:205], v171 offset:35840
	ds_read_b128 v[206:209], v171 offset:36864
	ds_read_b128 v[210:213], v171 offset:37888
	ds_read_b128 v[214:217], v171 offset:38912
	ds_read_b128 v[218:221], v171 offset:39936
	s_setprio 0
	s_waitcnt vmcnt(8)
	s_waitcnt lgkmcnt(0)
	s_barrier
	s_waitcnt lgkmcnt(0)
	v_mfma_f32_16x16x32_bf16 v[124:127], v[148:151], v[190:193], v[124:127]
	v_mfma_f32_16x16x32_bf16 v[124:127], v[152:155], v[194:197], v[124:127]
	v_mfma_f32_16x16x32_bf16 v[120:123], v[160:163], v[194:197], v[120:123]
	v_mfma_f32_16x16x32_bf16 v[120:123], v[156:159], v[190:193], v[120:123]
	v_mfma_f32_16x16x32_bf16 v[60:63], v[174:177], v[190:193], v[60:63]
	v_mfma_f32_16x16x32_bf16 v[60:63], v[178:181], v[194:197], v[60:63]
	v_mfma_f32_16x16x32_bf16 v[56:59], v[186:189], v[194:197], v[56:59]
	v_mfma_f32_16x16x32_bf16 v[56:59], v[182:185], v[190:193], v[56:59]
	v_mfma_f32_16x16x32_bf16 v[48:51], v[182:185], v[198:201], v[48:51]
	v_mfma_f32_16x16x32_bf16 v[48:51], v[186:189], v[202:205], v[48:51]
	v_mfma_f32_16x16x32_bf16 v[52:55], v[178:181], v[202:205], v[52:55]
	v_mfma_f32_16x16x32_bf16 v[52:55], v[174:177], v[198:201], v[52:55]
	v_mfma_f32_16x16x32_bf16 v[112:115], v[156:159], v[198:201], v[112:115]
	v_mfma_f32_16x16x32_bf16 v[112:115], v[160:163], v[202:205], v[112:115]
	v_mfma_f32_16x16x32_bf16 v[116:119], v[152:155], v[202:205], v[116:119]
	v_mfma_f32_16x16x32_bf16 v[116:119], v[148:151], v[198:201], v[116:119]
	v_mfma_f32_16x16x32_bf16 v[108:111], v[148:151], v[206:209], v[108:111]
	v_mfma_f32_16x16x32_bf16 v[108:111], v[152:155], v[210:213], v[108:111]
	v_mfma_f32_16x16x32_bf16 v[104:107], v[160:163], v[210:213], v[104:107]
	v_mfma_f32_16x16x32_bf16 v[104:107], v[156:159], v[206:209], v[104:107]
	v_mfma_f32_16x16x32_bf16 v[44:47], v[174:177], v[206:209], v[44:47]
	v_mfma_f32_16x16x32_bf16 v[44:47], v[178:181], v[210:213], v[44:47]
	v_mfma_f32_16x16x32_bf16 v[40:43], v[186:189], v[210:213], v[40:43]
	v_mfma_f32_16x16x32_bf16 v[40:43], v[182:185], v[206:209], v[40:43]
	v_mfma_f32_16x16x32_bf16 v[32:35], v[182:185], v[214:217], v[32:35]
	v_mfma_f32_16x16x32_bf16 v[32:35], v[186:189], v[218:221], v[32:35]
	v_mfma_f32_16x16x32_bf16 v[36:39], v[178:181], v[218:221], v[36:39]
	v_mfma_f32_16x16x32_bf16 v[36:39], v[174:177], v[214:217], v[36:39]
	v_mfma_f32_16x16x32_bf16 v[96:99], v[156:159], v[214:217], v[96:99]
	v_mfma_f32_16x16x32_bf16 v[96:99], v[160:163], v[218:221], v[96:99]
	v_mfma_f32_16x16x32_bf16 v[100:103], v[152:155], v[218:221], v[100:103]
	v_mfma_f32_16x16x32_bf16 v[100:103], v[148:151], v[214:217], v[100:103]
	s_barrier
	s_setprio 1
	s_add_i32 s28, s35, s36
	v_lshl_add_u64 v[190:191], v[222:223], 0, s[12:13]
	s_mov_b32 m0, s28
	s_nop 0
	global_load_lds_dwordx4 v[190:191], off
	s_add_i32 m0, s28, 0x2000
	s_add_u32 s26, s26, 0x100800
	v_lshl_add_u64 v[190:191], v[224:225], 0, s[12:13]
	s_addc_u32 s27, s27, 0
	s_add_i32 s28, s57, s36
	global_load_lds_dwordx4 v[190:191], off
	v_lshl_add_u64 v[190:191], s[26:27], 0, v[130:131]
	s_mov_b32 m0, s28
	s_nop 0
	global_load_lds_dwordx4 v[190:191], off
	v_lshl_add_u64 v[190:191], s[26:27], 0, v[134:135]
	s_add_i32 m0, s28, 0x2000
	s_nop 0
	global_load_lds_dwordx4 v[190:191], off
	v_lshl_add_u64 v[190:191], v[226:227], 0, s[12:13]
	s_mov_b32 m0, s49
	s_nop 0
	global_load_lds_dwordx4 v[190:191], off
	v_lshl_add_u64 v[190:191], v[228:229], 0, s[12:13]
	s_mov_b32 m0, s50
	s_nop 0
	global_load_lds_dwordx4 v[190:191], off
	ds_read_b128 v[190:193], v171 offset:49152
	ds_read_b128 v[194:197], v171 offset:50176
	ds_read_b128 v[198:201], v171 offset:51200
	ds_read_b128 v[202:205], v171 offset:52224
	ds_read_b128 v[206:209], v171 offset:53248
	ds_read_b128 v[210:213], v171 offset:54272
	ds_read_b128 v[214:217], v171 offset:55296
	ds_read_b128 v[218:221], v171 offset:56320
	s_setprio 0
	s_waitcnt vmcnt(8)
	s_waitcnt lgkmcnt(0)
	s_barrier
	s_waitcnt lgkmcnt(0)
	v_mfma_f32_16x16x32_bf16 v[92:95], v[148:151], v[190:193], v[92:95]
	v_mfma_f32_16x16x32_bf16 v[92:95], v[152:155], v[194:197], v[92:95]
	v_mfma_f32_16x16x32_bf16 v[88:91], v[160:163], v[194:197], v[88:91]
	v_mfma_f32_16x16x32_bf16 v[88:91], v[156:159], v[190:193], v[88:91]
	v_mfma_f32_16x16x32_bf16 v[28:31], v[174:177], v[190:193], v[28:31]
	v_mfma_f32_16x16x32_bf16 v[28:31], v[178:181], v[194:197], v[28:31]
	v_mfma_f32_16x16x32_bf16 v[24:27], v[186:189], v[194:197], v[24:27]
	v_mfma_f32_16x16x32_bf16 v[24:27], v[182:185], v[190:193], v[24:27]
	v_mfma_f32_16x16x32_bf16 v[16:19], v[182:185], v[198:201], v[16:19]
	v_mfma_f32_16x16x32_bf16 v[16:19], v[186:189], v[202:205], v[16:19]
	v_mfma_f32_16x16x32_bf16 v[20:23], v[178:181], v[202:205], v[20:23]
	v_mfma_f32_16x16x32_bf16 v[20:23], v[174:177], v[198:201], v[20:23]
	v_mfma_f32_16x16x32_bf16 v[80:83], v[156:159], v[198:201], v[80:83]
	v_mfma_f32_16x16x32_bf16 v[80:83], v[160:163], v[202:205], v[80:83]
	v_mfma_f32_16x16x32_bf16 v[84:87], v[152:155], v[202:205], v[84:87]
	v_mfma_f32_16x16x32_bf16 v[84:87], v[148:151], v[198:201], v[84:87]
	v_mfma_f32_16x16x32_bf16 v[76:79], v[148:151], v[206:209], v[76:79]
	v_mfma_f32_16x16x32_bf16 v[76:79], v[152:155], v[210:213], v[76:79]
	v_mfma_f32_16x16x32_bf16 v[72:75], v[160:163], v[210:213], v[72:75]
	v_mfma_f32_16x16x32_bf16 v[72:75], v[156:159], v[206:209], v[72:75]
	v_mfma_f32_16x16x32_bf16 v[12:15], v[174:177], v[206:209], v[12:15]
	v_mfma_f32_16x16x32_bf16 v[12:15], v[178:181], v[210:213], v[12:15]
	v_mfma_f32_16x16x32_bf16 v[8:11], v[186:189], v[210:213], v[8:11]
	v_mfma_f32_16x16x32_bf16 v[8:11], v[182:185], v[206:209], v[8:11]
	v_mfma_f32_16x16x32_bf16 v[0:3], v[182:185], v[214:217], v[0:3]
	v_mfma_f32_16x16x32_bf16 v[0:3], v[186:189], v[218:221], v[0:3]
	v_mfma_f32_16x16x32_bf16 v[4:7], v[178:181], v[218:221], v[4:7]
	v_mfma_f32_16x16x32_bf16 v[4:7], v[174:177], v[214:217], v[4:7]
	v_mfma_f32_16x16x32_bf16 v[64:67], v[156:159], v[214:217], v[64:67]
	v_mfma_f32_16x16x32_bf16 v[64:67], v[160:163], v[218:221], v[64:67]
	v_mfma_f32_16x16x32_bf16 v[68:71], v[152:155], v[218:221], v[68:71]
	v_mfma_f32_16x16x32_bf16 v[68:71], v[148:151], v[214:217], v[68:71]
	s_barrier
	s_setprio 1
	s_add_i32 s34, s34, 2
	s_add_u32 s6, s6, 0x1000
	s_addc_u32 s7, s7, 0
	s_add_u32 s30, s30, 0x1000
	s_addc_u32 s31, s31, 0
	s_cmp_gt_u32 s34, 61
	s_cbranch_scc0 .LBB0_200
	s_setprio 0
	s_and_b64 vcc, exec, s[0:1]
	s_cbranch_vccz .LBB0_203
	s_barrier

.LBB0_333:
	ds_read_b128 v[144:147], v152
	ds_read_b128 v[156:159], v152 offset:1024
	ds_read_b128 v[160:163], v152 offset:2048
	ds_read_b128 v[164:167], v152 offset:3072
	ds_read_b128 v[168:171], v153
	ds_read_b128 v[172:175], v153 offset:1024
	ds_read_b128 v[176:179], v153 offset:2048
	ds_read_b128 v[180:183], v153 offset:3072
	s_add_u32 s28, s24, 0x100
	s_addc_u32 s29, s25, 0
	s_cmp_eq_u32 s56, 60
	s_cselect_b32 s35, s13, s29
	s_cselect_b32 s34, s52, s28
	s_cselect_b32 s31, s11, s55
	s_cselect_b32 s30, s53, s54
	v_lshl_add_u64 v[184:185], s[24:25], 0, v[136:137]
	s_add_i32 m0, s21, 0xc000
	s_nop 0
	global_load_lds_dwordx4 v[184:185], off
	v_lshl_add_u64 v[184:185], s[24:25], 0, v[138:139]
	s_add_i32 m0, s21, 0xe000
	s_nop 0
	global_load_lds_dwordx4 v[184:185], off
	ds_read_b128 v[184:187], v154
	ds_read_b128 v[188:191], v154 offset:1024
	ds_read_b128 v[192:195], v154 offset:2048
	ds_read_b128 v[196:199], v154 offset:3072
	ds_read_b128 v[200:203], v154 offset:4096
	ds_read_b128 v[204:207], v154 offset:5120
	ds_read_b128 v[208:211], v154 offset:6144
	ds_read_b128 v[212:215], v154 offset:7168
	s_setprio 0
	s_waitcnt vmcnt(8)
	s_waitcnt lgkmcnt(0)
	s_barrier
	s_waitcnt lgkmcnt(0)
	v_mfma_f32_16x16x32_bf16 v[124:127], v[144:147], v[184:187], v[124:127]
	v_mfma_f32_16x16x32_bf16 v[124:127], v[156:159], v[188:191], v[124:127]
	v_mfma_f32_16x16x32_bf16 v[120:123], v[164:167], v[188:191], v[120:123]
	v_mfma_f32_16x16x32_bf16 v[120:123], v[160:163], v[184:187], v[120:123]
	v_mfma_f32_16x16x32_bf16 v[112:115], v[168:171], v[184:187], v[112:115]
	v_mfma_f32_16x16x32_bf16 v[112:115], v[172:175], v[188:191], v[112:115]
	v_mfma_f32_16x16x32_bf16 v[104:107], v[180:183], v[188:191], v[104:107]
	v_mfma_f32_16x16x32_bf16 v[104:107], v[176:179], v[184:187], v[104:107]
	v_mfma_f32_16x16x32_bf16 v[88:91], v[176:179], v[192:195], v[88:91]
	v_mfma_f32_16x16x32_bf16 v[88:91], v[180:183], v[196:199], v[88:91]
	v_mfma_f32_16x16x32_bf16 v[96:99], v[172:175], v[196:199], v[96:99]
	v_mfma_f32_16x16x32_bf16 v[96:99], v[168:171], v[192:195], v[96:99]
	v_mfma_f32_16x16x32_bf16 v[108:111], v[160:163], v[192:195], v[108:111]
	v_mfma_f32_16x16x32_bf16 v[108:111], v[164:167], v[196:199], v[108:111]
	v_mfma_f32_16x16x32_bf16 v[116:119], v[156:159], v[196:199], v[116:119]
	v_mfma_f32_16x16x32_bf16 v[116:119], v[144:147], v[192:195], v[116:119]
	v_mfma_f32_16x16x32_bf16 v[100:103], v[144:147], v[200:203], v[100:103]
	v_mfma_f32_16x16x32_bf16 v[100:103], v[156:159], v[204:207], v[100:103]
	v_mfma_f32_16x16x32_bf16 v[92:95], v[164:167], v[204:207], v[92:95]
	v_mfma_f32_16x16x32_bf16 v[92:95], v[160:163], v[200:203], v[92:95]
	v_mfma_f32_16x16x32_bf16 v[80:83], v[168:171], v[200:203], v[80:83]
	v_mfma_f32_16x16x32_bf16 v[80:83], v[172:175], v[204:207], v[80:83]
	v_mfma_f32_16x16x32_bf16 v[72:75], v[180:183], v[204:207], v[72:75]
	v_mfma_f32_16x16x32_bf16 v[72:75], v[176:179], v[200:203], v[72:75]
	v_mfma_f32_16x16x32_bf16 v[64:67], v[176:179], v[208:211], v[64:67]
	v_mfma_f32_16x16x32_bf16 v[64:67], v[180:183], v[212:215], v[64:67]
	v_mfma_f32_16x16x32_bf16 v[68:71], v[172:175], v[212:215], v[68:71]
	v_mfma_f32_16x16x32_bf16 v[68:71], v[168:171], v[208:211], v[68:71]
	v_mfma_f32_16x16x32_bf16 v[76:79], v[160:163], v[208:211], v[76:79]
	v_mfma_f32_16x16x32_bf16 v[76:79], v[164:167], v[212:215], v[76:79]
	v_mfma_f32_16x16x32_bf16 v[84:87], v[156:159], v[212:215], v[84:87]
	v_mfma_f32_16x16x32_bf16 v[84:87], v[144:147], v[208:211], v[84:87]
	s_barrier
	s_setprio 1
	s_add_i32 s24, s49, s41
	v_lshl_add_u64 v[216:217], s[30:31], 0, v[130:131]
	s_mov_b32 m0, s24
	v_lshl_add_u64 v[218:219], s[30:31], 0, v[134:135]
	global_load_lds_dwordx4 v[216:217], off
	s_add_i32 m0, s24, 0x2000
	s_add_u32 s24, s30, 0x100000
	s_addc_u32 s25, s31, 0
	s_add_i32 s57, s50, s41
	global_load_lds_dwordx4 v[218:219], off
	v_lshl_add_u64 v[184:185], s[24:25], 0, v[130:131]
	s_mov_b32 m0, s57
	v_lshl_add_u64 v[220:221], s[34:35], 0, v[128:129]
	global_load_lds_dwordx4 v[184:185], off
	v_lshl_add_u64 v[184:185], s[24:25], 0, v[134:135]
	s_add_i32 m0, s57, 0x2000
	v_lshl_add_u64 v[222:223], s[34:35], 0, v[132:133]
	global_load_lds_dwordx4 v[184:185], off
	s_mov_b32 m0, s21
	s_nop 0
	global_load_lds_dwordx4 v[220:221], off
	s_mov_b32 m0, s42
	s_nop 0
	global_load_lds_dwordx4 v[222:223], off
	ds_read_b128 v[184:187], v154 offset:16384
	ds_read_b128 v[188:191], v154 offset:17408
	ds_read_b128 v[192:195], v154 offset:18432
	ds_read_b128 v[196:199], v154 offset:19456
	ds_read_b128 v[200:203], v154 offset:20480
	ds_read_b128 v[204:207], v154 offset:21504
	ds_read_b128 v[208:211], v154 offset:22528
	ds_read_b128 v[212:215], v154 offset:23552
	s_setprio 0
	s_waitcnt vmcnt(8)
	s_waitcnt lgkmcnt(0)
	s_barrier
	s_waitcnt lgkmcnt(0)
	v_mfma_f32_16x16x32_bf16 v[60:63], v[144:147], v[184:187], v[60:63]
	v_mfma_f32_16x16x32_bf16 v[60:63], v[156:159], v[188:191], v[60:63]
	v_mfma_f32_16x16x32_bf16 v[56:59], v[164:167], v[188:191], v[56:59]
	v_mfma_f32_16x16x32_bf16 v[56:59], v[160:163], v[184:187], v[56:59]
	v_mfma_f32_16x16x32_bf16 v[48:51], v[168:171], v[184:187], v[48:51]
	v_mfma_f32_16x16x32_bf16 v[48:51], v[172:175], v[188:191], v[48:51]
	v_mfma_f32_16x16x32_bf16 v[40:43], v[180:183], v[188:191], v[40:43]
	v_mfma_f32_16x16x32_bf16 v[40:43], v[176:179], v[184:187], v[40:43]
	v_mfma_f32_16x16x32_bf16 v[24:27], v[176:179], v[192:195], v[24:27]
	v_mfma_f32_16x16x32_bf16 v[24:27], v[180:183], v[196:199], v[24:27]
	v_mfma_f32_16x16x32_bf16 v[32:35], v[172:175], v[196:199], v[32:35]
	v_mfma_f32_16x16x32_bf16 v[32:35], v[168:171], v[192:195], v[32:35]
	v_mfma_f32_16x16x32_bf16 v[44:47], v[160:163], v[192:195], v[44:47]
	v_mfma_f32_16x16x32_bf16 v[44:47], v[164:167], v[196:199], v[44:47]
	v_mfma_f32_16x16x32_bf16 v[52:55], v[156:159], v[196:199], v[52:55]
	v_mfma_f32_16x16x32_bf16 v[52:55], v[144:147], v[192:195], v[52:55]
	v_mfma_f32_16x16x32_bf16 v[36:39], v[144:147], v[200:203], v[36:39]
	v_mfma_f32_16x16x32_bf16 v[36:39], v[156:159], v[204:207], v[36:39]
	v_mfma_f32_16x16x32_bf16 v[28:31], v[164:167], v[204:207], v[28:31]
	v_mfma_f32_16x16x32_bf16 v[28:31], v[160:163], v[200:203], v[28:31]
	v_mfma_f32_16x16x32_bf16 v[16:19], v[168:171], v[200:203], v[16:19]
	v_mfma_f32_16x16x32_bf16 v[16:19], v[172:175], v[204:207], v[16:19]
	v_mfma_f32_16x16x32_bf16 v[8:11], v[180:183], v[204:207], v[8:11]
	v_mfma_f32_16x16x32_bf16 v[8:11], v[176:179], v[200:203], v[8:11]
	v_mfma_f32_16x16x32_bf16 v[0:3], v[176:179], v[208:211], v[0:3]
	v_mfma_f32_16x16x32_bf16 v[0:3], v[180:183], v[212:215], v[0:3]
	v_mfma_f32_16x16x32_bf16 v[4:7], v[172:175], v[212:215], v[4:7]
	v_mfma_f32_16x16x32_bf16 v[4:7], v[168:171], v[208:211], v[4:7]
	v_mfma_f32_16x16x32_bf16 v[12:15], v[160:163], v[208:211], v[12:15]
	v_mfma_f32_16x16x32_bf16 v[12:15], v[164:167], v[212:215], v[12:15]
	v_mfma_f32_16x16x32_bf16 v[20:23], v[156:159], v[212:215], v[20:23]
	v_mfma_f32_16x16x32_bf16 v[20:23], v[144:147], v[208:211], v[20:23]
	s_barrier
	s_setprio 1
	s_add_i32 s57, 0, 0x18000
	v_add_u32_e32 v155, s57, v149
	s_add_i32 s58, 0, 0x1c000
	ds_read_b128 v[144:147], v155
	ds_read_b128 v[156:159], v155 offset:1024
	ds_read_b128 v[160:163], v155 offset:2048
	ds_read_b128 v[164:167], v155 offset:3072
	v_add_u32_e32 v155, s58, v149
	ds_read_b128 v[168:171], v155
	ds_read_b128 v[172:175], v155 offset:1024
	ds_read_b128 v[176:179], v155 offset:2048
	ds_read_b128 v[180:183], v155 offset:3072
	s_add_u32 s24, s34, 0x100000
	s_addc_u32 s25, s35, 0
	s_mov_b32 m0, s43
	v_lshl_add_u64 v[184:185], s[24:25], 0, v[128:129]
	global_load_lds_dwordx4 v[184:185], off
	v_lshl_add_u64 v[184:185], s[24:25], 0, v[132:133]
	s_mov_b32 m0, s44
	s_nop 0
	global_load_lds_dwordx4 v[184:185], off
	ds_read_b128 v[184:187], v154 offset:32768
	ds_read_b128 v[188:191], v154 offset:33792
	ds_read_b128 v[192:195], v154 offset:34816
	ds_read_b128 v[196:199], v154 offset:35840
	ds_read_b128 v[200:203], v154 offset:36864
	ds_read_b128 v[204:207], v154 offset:37888
	ds_read_b128 v[208:211], v154 offset:38912
	ds_read_b128 v[212:215], v154 offset:39936
	s_setprio 0
	s_waitcnt vmcnt(8)
	s_waitcnt lgkmcnt(0)
	s_barrier
	s_waitcnt lgkmcnt(0)
	v_mfma_f32_16x16x32_bf16 v[124:127], v[144:147], v[184:187], v[124:127]
	v_mfma_f32_16x16x32_bf16 v[124:127], v[156:159], v[188:191], v[124:127]
	v_mfma_f32_16x16x32_bf16 v[120:123], v[164:167], v[188:191], v[120:123]
	v_mfma_f32_16x16x32_bf16 v[120:123], v[160:163], v[184:187], v[120:123]
	v_mfma_f32_16x16x32_bf16 v[112:115], v[168:171], v[184:187], v[112:115]
	v_mfma_f32_16x16x32_bf16 v[112:115], v[172:175], v[188:191], v[112:115]
	v_mfma_f32_16x16x32_bf16 v[104:107], v[180:183], v[188:191], v[104:107]
	v_mfma_f32_16x16x32_bf16 v[104:107], v[176:179], v[184:187], v[104:107]
	v_mfma_f32_16x16x32_bf16 v[88:91], v[176:179], v[192:195], v[88:91]
	v_mfma_f32_16x16x32_bf16 v[88:91], v[180:183], v[196:199], v[88:91]
	v_mfma_f32_16x16x32_bf16 v[96:99], v[172:175], v[196:199], v[96:99]
	v_mfma_f32_16x16x32_bf16 v[96:99], v[168:171], v[192:195], v[96:99]
	v_mfma_f32_16x16x32_bf16 v[108:111], v[160:163], v[192:195], v[108:111]
	v_mfma_f32_16x16x32_bf16 v[108:111], v[164:167], v[196:199], v[108:111]
	v_mfma_f32_16x16x32_bf16 v[116:119], v[156:159], v[196:199], v[116:119]
	v_mfma_f32_16x16x32_bf16 v[116:119], v[144:147], v[192:195], v[116:119]
	v_mfma_f32_16x16x32_bf16 v[100:103], v[144:147], v[200:203], v[100:103]
	v_mfma_f32_16x16x32_bf16 v[100:103], v[156:159], v[204:207], v[100:103]
	v_mfma_f32_16x16x32_bf16 v[92:95], v[164:167], v[204:207], v[92:95]
	v_mfma_f32_16x16x32_bf16 v[92:95], v[160:163], v[200:203], v[92:95]
	v_mfma_f32_16x16x32_bf16 v[80:83], v[168:171], v[200:203], v[80:83]
	v_mfma_f32_16x16x32_bf16 v[80:83], v[172:175], v[204:207], v[80:83]
	v_mfma_f32_16x16x32_bf16 v[72:75], v[180:183], v[204:207], v[72:75]
	v_mfma_f32_16x16x32_bf16 v[72:75], v[176:179], v[200:203], v[72:75]
	v_mfma_f32_16x16x32_bf16 v[64:67], v[176:179], v[208:211], v[64:67]
	v_mfma_f32_16x16x32_bf16 v[64:67], v[180:183], v[212:215], v[64:67]
	v_mfma_f32_16x16x32_bf16 v[68:71], v[172:175], v[212:215], v[68:71]
	v_mfma_f32_16x16x32_bf16 v[68:71], v[168:171], v[208:211], v[68:71]
	v_mfma_f32_16x16x32_bf16 v[76:79], v[160:163], v[208:211], v[76:79]
	v_mfma_f32_16x16x32_bf16 v[76:79], v[164:167], v[212:215], v[76:79]
	v_mfma_f32_16x16x32_bf16 v[84:87], v[156:159], v[212:215], v[84:87]
	v_mfma_f32_16x16x32_bf16 v[84:87], v[144:147], v[208:211], v[84:87]
	s_barrier
	s_setprio 1
	s_add_i32 s24, s57, s41
	v_lshl_add_u64 v[184:185], v[216:217], 0, s[8:9]
	s_mov_b32 m0, s24
	s_nop 0
	global_load_lds_dwordx4 v[184:185], off
	s_add_i32 m0, s24, 0x2000
	s_add_u32 s24, s30, 0x100080
	v_lshl_add_u64 v[184:185], v[218:219], 0, s[8:9]
	s_addc_u32 s25, s31, 0
	s_add_i32 s30, s58, s41
	global_load_lds_dwordx4 v[184:185], off
	v_lshl_add_u64 v[184:185], s[24:25], 0, v[130:131]
	s_mov_b32 m0, s30
	s_nop 0
	global_load_lds_dwordx4 v[184:185], off
	v_lshl_add_u64 v[184:185], s[24:25], 0, v[134:135]
	s_add_i32 m0, s30, 0x2000
	s_nop 0
	global_load_lds_dwordx4 v[184:185], off
	v_lshl_add_u64 v[184:185], v[220:221], 0, s[8:9]
	s_mov_b32 m0, s46
	s_nop 0
	global_load_lds_dwordx4 v[184:185], off
	v_lshl_add_u64 v[184:185], v[222:223], 0, s[8:9]
	s_mov_b32 m0, s47
	s_nop 0
	global_load_lds_dwordx4 v[184:185], off
	ds_read_b128 v[184:187], v154 offset:49152
	ds_read_b128 v[188:191], v154 offset:50176
	ds_read_b128 v[192:195], v154 offset:51200
	ds_read_b128 v[196:199], v154 offset:52224
	ds_read_b128 v[200:203], v154 offset:53248
	ds_read_b128 v[204:207], v154 offset:54272
	ds_read_b128 v[208:211], v154 offset:55296
	ds_read_b128 v[212:215], v154 offset:56320
	s_setprio 0
	s_waitcnt vmcnt(8)
	s_waitcnt lgkmcnt(0)
	s_barrier
	s_waitcnt lgkmcnt(0)
	v_mfma_f32_16x16x32_bf16 v[60:63], v[144:147], v[184:187], v[60:63]
	v_mfma_f32_16x16x32_bf16 v[60:63], v[156:159], v[188:191], v[60:63]
	v_mfma_f32_16x16x32_bf16 v[56:59], v[164:167], v[188:191], v[56:59]
	v_mfma_f32_16x16x32_bf16 v[56:59], v[160:163], v[184:187], v[56:59]
	v_mfma_f32_16x16x32_bf16 v[48:51], v[168:171], v[184:187], v[48:51]
	v_mfma_f32_16x16x32_bf16 v[48:51], v[172:175], v[188:191], v[48:51]
	v_mfma_f32_16x16x32_bf16 v[40:43], v[180:183], v[188:191], v[40:43]
	v_mfma_f32_16x16x32_bf16 v[40:43], v[176:179], v[184:187], v[40:43]
	v_mfma_f32_16x16x32_bf16 v[24:27], v[176:179], v[192:195], v[24:27]
	v_mfma_f32_16x16x32_bf16 v[24:27], v[180:183], v[196:199], v[24:27]
	v_mfma_f32_16x16x32_bf16 v[32:35], v[172:175], v[196:199], v[32:35]
	v_mfma_f32_16x16x32_bf16 v[32:35], v[168:171], v[192:195], v[32:35]
	v_mfma_f32_16x16x32_bf16 v[44:47], v[160:163], v[192:195], v[44:47]
	v_mfma_f32_16x16x32_bf16 v[44:47], v[164:167], v[196:199], v[44:47]
	v_mfma_f32_16x16x32_bf16 v[52:55], v[156:159], v[196:199], v[52:55]
	v_mfma_f32_16x16x32_bf16 v[52:55], v[144:147], v[192:195], v[52:55]
	v_mfma_f32_16x16x32_bf16 v[36:39], v[144:147], v[200:203], v[36:39]
	v_mfma_f32_16x16x32_bf16 v[36:39], v[156:159], v[204:207], v[36:39]
	v_mfma_f32_16x16x32_bf16 v[28:31], v[164:167], v[204:207], v[28:31]
	v_mfma_f32_16x16x32_bf16 v[28:31], v[160:163], v[200:203], v[28:31]
	v_mfma_f32_16x16x32_bf16 v[16:19], v[168:171], v[200:203], v[16:19]
	v_mfma_f32_16x16x32_bf16 v[16:19], v[172:175], v[204:207], v[16:19]
	v_mfma_f32_16x16x32_bf16 v[8:11], v[180:183], v[204:207], v[8:11]
	v_mfma_f32_16x16x32_bf16 v[8:11], v[176:179], v[200:203], v[8:11]
	v_mfma_f32_16x16x32_bf16 v[0:3], v[176:179], v[208:211], v[0:3]
	v_mfma_f32_16x16x32_bf16 v[0:3], v[180:183], v[212:215], v[0:3]
	v_mfma_f32_16x16x32_bf16 v[4:7], v[172:175], v[212:215], v[4:7]
	v_mfma_f32_16x16x32_bf16 v[4:7], v[168:171], v[208:211], v[4:7]
	v_mfma_f32_16x16x32_bf16 v[12:15], v[160:163], v[208:211], v[12:15]
	v_mfma_f32_16x16x32_bf16 v[12:15], v[164:167], v[212:215], v[12:15]
	v_mfma_f32_16x16x32_bf16 v[20:23], v[156:159], v[212:215], v[20:23]
	v_mfma_f32_16x16x32_bf16 v[20:23], v[144:147], v[208:211], v[20:23]
	s_barrier
	s_setprio 1
	s_add_i32 s56, s56, 2
	s_add_u32 s54, s54, 0x100
	s_addc_u32 s55, s55, 0
	s_cmp_gt_u32 s56, 61
	s_mov_b64 s[24:25], s[28:29]
	s_cbranch_scc0 .LBB0_333
	s_setprio 0
	s_and_b64 vcc, exec, s[0:1]
	s_cbranch_vccz .LBB0_336
	s_barrier

.LBB0_1202:
	ds_read_b128 v[128:131], v176
	ds_read_b128 v[132:135], v176 offset:1024
	ds_read_b128 v[136:139], v176 offset:2048
	ds_read_b128 v[140:143], v176 offset:3072
	ds_read_b128 v[144:147], v177
	ds_read_b128 v[148:151], v177 offset:1024
	ds_read_b128 v[180:183], v177 offset:2048
	ds_read_b128 v[184:187], v177 offset:3072
	s_add_u32 s30, s28, 0xfff00080
	s_addc_u32 s31, s29, -1
	s_cmp_eq_u32 s40, 60
	s_cselect_b32 s35, s23, s31
	s_cselect_b32 s34, s36, s30
	s_cselect_b32 s31, s21, s39
	s_cselect_b32 s30, s37, s38
	v_lshl_add_u64 v[172:173], s[28:29], 0, v[164:165]
	s_add_i32 m0, s7, 0xc000
	s_nop 0
	global_load_lds_dwordx4 v[172:173], off
	v_lshl_add_u64 v[172:173], s[28:29], 0, v[166:167]
	s_add_i32 m0, s7, 0xe000
	s_nop 0
	global_load_lds_dwordx4 v[172:173], off
	ds_read_b128 v[188:191], v178
	ds_read_b128 v[192:195], v178 offset:1024
	ds_read_b128 v[196:199], v178 offset:2048
	ds_read_b128 v[200:203], v178 offset:3072
	ds_read_b128 v[204:207], v178 offset:4096
	ds_read_b128 v[208:211], v178 offset:5120
	ds_read_b128 v[212:215], v178 offset:6144
	ds_read_b128 v[216:219], v178 offset:7168
	s_setprio 0
	s_waitcnt vmcnt(8)
	s_waitcnt lgkmcnt(0)
	s_barrier
	s_waitcnt lgkmcnt(0)
	v_mfma_f32_16x16x32_bf16 v[124:127], v[128:131], v[188:191], v[124:127]
	v_mfma_f32_16x16x32_bf16 v[124:127], v[132:135], v[192:195], v[124:127]
	v_mfma_f32_16x16x32_bf16 v[120:123], v[140:143], v[192:195], v[120:123]
	v_mfma_f32_16x16x32_bf16 v[120:123], v[136:139], v[188:191], v[120:123]
	v_mfma_f32_16x16x32_bf16 v[116:119], v[144:147], v[188:191], v[116:119]
	v_mfma_f32_16x16x32_bf16 v[116:119], v[148:151], v[192:195], v[116:119]
	v_mfma_f32_16x16x32_bf16 v[112:115], v[184:187], v[192:195], v[112:115]
	v_mfma_f32_16x16x32_bf16 v[112:115], v[180:183], v[188:191], v[112:115]
	v_mfma_f32_16x16x32_bf16 v[96:99], v[180:183], v[196:199], v[96:99]
	v_mfma_f32_16x16x32_bf16 v[96:99], v[184:187], v[200:203], v[96:99]
	v_mfma_f32_16x16x32_bf16 v[100:103], v[148:151], v[200:203], v[100:103]
	v_mfma_f32_16x16x32_bf16 v[100:103], v[144:147], v[196:199], v[100:103]
	v_mfma_f32_16x16x32_bf16 v[104:107], v[136:139], v[196:199], v[104:107]
	v_mfma_f32_16x16x32_bf16 v[104:107], v[140:143], v[200:203], v[104:107]
	v_mfma_f32_16x16x32_bf16 v[108:111], v[132:135], v[200:203], v[108:111]
	v_mfma_f32_16x16x32_bf16 v[108:111], v[128:131], v[196:199], v[108:111]
	v_mfma_f32_16x16x32_bf16 v[92:95], v[128:131], v[204:207], v[92:95]
	v_mfma_f32_16x16x32_bf16 v[92:95], v[132:135], v[208:211], v[92:95]
	v_mfma_f32_16x16x32_bf16 v[88:91], v[140:143], v[208:211], v[88:91]
	v_mfma_f32_16x16x32_bf16 v[88:91], v[136:139], v[204:207], v[88:91]
	v_mfma_f32_16x16x32_bf16 v[84:87], v[144:147], v[204:207], v[84:87]
	v_mfma_f32_16x16x32_bf16 v[84:87], v[148:151], v[208:211], v[84:87]
	v_mfma_f32_16x16x32_bf16 v[80:83], v[184:187], v[208:211], v[80:83]
	v_mfma_f32_16x16x32_bf16 v[80:83], v[180:183], v[204:207], v[80:83]
	v_mfma_f32_16x16x32_bf16 v[64:67], v[180:183], v[212:215], v[64:67]
	v_mfma_f32_16x16x32_bf16 v[64:67], v[184:187], v[216:219], v[64:67]
	v_mfma_f32_16x16x32_bf16 v[68:71], v[148:151], v[216:219], v[68:71]
	v_mfma_f32_16x16x32_bf16 v[68:71], v[144:147], v[212:215], v[68:71]
	v_mfma_f32_16x16x32_bf16 v[72:75], v[136:139], v[212:215], v[72:75]
	v_mfma_f32_16x16x32_bf16 v[72:75], v[140:143], v[216:219], v[72:75]
	v_mfma_f32_16x16x32_bf16 v[76:79], v[132:135], v[216:219], v[76:79]
	v_mfma_f32_16x16x32_bf16 v[76:79], v[128:131], v[212:215], v[76:79]
	s_barrier
	s_setprio 1
	s_add_i32 s41, s68, s33
	v_lshl_add_u64 v[172:173], s[30:31], 0, v[154:155]
	s_mov_b32 m0, s41
	v_lshl_add_u64 v[220:221], s[30:31], 0, v[158:159]
	global_load_lds_dwordx4 v[172:173], off
	s_add_i32 m0, s41, 0x2000
	s_add_u32 s42, s30, 0x100000
	s_addc_u32 s43, s31, 0
	s_add_i32 s41, s69, s33
	global_load_lds_dwordx4 v[220:221], off
	v_lshl_add_u64 v[188:189], s[42:43], 0, v[154:155]
	s_mov_b32 m0, s41
	v_lshl_add_u64 v[222:223], s[34:35], 0, v[152:153]
	global_load_lds_dwordx4 v[188:189], off
	v_lshl_add_u64 v[188:189], s[42:43], 0, v[158:159]
	s_add_i32 m0, s41, 0x2000
	v_lshl_add_u64 v[224:225], s[34:35], 0, v[156:157]
	global_load_lds_dwordx4 v[188:189], off
	s_mov_b32 m0, s7
	s_nop 0
	global_load_lds_dwordx4 v[222:223], off
	s_mov_b32 m0, s59
	s_nop 0
	global_load_lds_dwordx4 v[224:225], off
	ds_read_b128 v[188:191], v178 offset:16384
	ds_read_b128 v[192:195], v178 offset:17408
	ds_read_b128 v[196:199], v178 offset:18432
	ds_read_b128 v[200:203], v178 offset:19456
	ds_read_b128 v[204:207], v178 offset:20480
	ds_read_b128 v[208:211], v178 offset:21504
	ds_read_b128 v[212:215], v178 offset:22528
	ds_read_b128 v[216:219], v178 offset:23552
	s_setprio 0
	s_waitcnt vmcnt(8)
	s_waitcnt lgkmcnt(0)
	s_barrier
	s_waitcnt lgkmcnt(0)
	v_mfma_f32_16x16x32_bf16 v[60:63], v[128:131], v[188:191], v[60:63]
	v_mfma_f32_16x16x32_bf16 v[60:63], v[132:135], v[192:195], v[60:63]
	v_mfma_f32_16x16x32_bf16 v[56:59], v[140:143], v[192:195], v[56:59]
	v_mfma_f32_16x16x32_bf16 v[56:59], v[136:139], v[188:191], v[56:59]
	v_mfma_f32_16x16x32_bf16 v[52:55], v[144:147], v[188:191], v[52:55]
	v_mfma_f32_16x16x32_bf16 v[52:55], v[148:151], v[192:195], v[52:55]
	v_mfma_f32_16x16x32_bf16 v[48:51], v[184:187], v[192:195], v[48:51]
	v_mfma_f32_16x16x32_bf16 v[48:51], v[180:183], v[188:191], v[48:51]
	v_mfma_f32_16x16x32_bf16 v[32:35], v[180:183], v[196:199], v[32:35]
	v_mfma_f32_16x16x32_bf16 v[32:35], v[184:187], v[200:203], v[32:35]
	v_mfma_f32_16x16x32_bf16 v[36:39], v[148:151], v[200:203], v[36:39]
	v_mfma_f32_16x16x32_bf16 v[36:39], v[144:147], v[196:199], v[36:39]
	v_mfma_f32_16x16x32_bf16 v[40:43], v[136:139], v[196:199], v[40:43]
	v_mfma_f32_16x16x32_bf16 v[40:43], v[140:143], v[200:203], v[40:43]
	v_mfma_f32_16x16x32_bf16 v[44:47], v[132:135], v[200:203], v[44:47]
	v_mfma_f32_16x16x32_bf16 v[44:47], v[128:131], v[196:199], v[44:47]
	v_mfma_f32_16x16x32_bf16 v[28:31], v[128:131], v[204:207], v[28:31]
	v_mfma_f32_16x16x32_bf16 v[28:31], v[132:135], v[208:211], v[28:31]
	v_mfma_f32_16x16x32_bf16 v[24:27], v[140:143], v[208:211], v[24:27]
	v_mfma_f32_16x16x32_bf16 v[24:27], v[136:139], v[204:207], v[24:27]
	v_mfma_f32_16x16x32_bf16 v[20:23], v[144:147], v[204:207], v[20:23]
	v_mfma_f32_16x16x32_bf16 v[20:23], v[148:151], v[208:211], v[20:23]
	v_mfma_f32_16x16x32_bf16 v[16:19], v[184:187], v[208:211], v[16:19]
	v_mfma_f32_16x16x32_bf16 v[16:19], v[180:183], v[204:207], v[16:19]
	v_mfma_f32_16x16x32_bf16 v[0:3], v[180:183], v[212:215], v[0:3]
	v_mfma_f32_16x16x32_bf16 v[0:3], v[184:187], v[216:219], v[0:3]
	v_mfma_f32_16x16x32_bf16 v[4:7], v[148:151], v[216:219], v[4:7]
	v_mfma_f32_16x16x32_bf16 v[4:7], v[144:147], v[212:215], v[4:7]
	v_mfma_f32_16x16x32_bf16 v[8:11], v[136:139], v[212:215], v[8:11]
	v_mfma_f32_16x16x32_bf16 v[8:11], v[140:143], v[216:219], v[8:11]
	v_mfma_f32_16x16x32_bf16 v[12:15], v[132:135], v[216:219], v[12:15]
	v_mfma_f32_16x16x32_bf16 v[12:15], v[128:131], v[212:215], v[12:15]
	s_barrier
	s_setprio 1
	s_add_i32 s41, 0, 0x18000
	s_add_i32 s42, 0, 0x1c000
	v_add_u32_e32 v140, s41, v174
	v_add_u32_e32 v184, s42, v174
	ds_read_b128 v[128:131], v140
	ds_read_b128 v[132:135], v140 offset:1024
	ds_read_b128 v[136:139], v140 offset:2048
	ds_read_b128 v[140:143], v140 offset:3072
	ds_read_b128 v[144:147], v184
	ds_read_b128 v[148:151], v184 offset:1024
	ds_read_b128 v[180:183], v184 offset:2048
	ds_read_b128 v[184:187], v184 offset:3072
	s_add_u32 s34, s34, 0x100000
	s_addc_u32 s35, s35, 0
	s_mov_b32 m0, s60
	v_lshl_add_u64 v[188:189], s[34:35], 0, v[152:153]
	global_load_lds_dwordx4 v[188:189], off
	v_lshl_add_u64 v[188:189], s[34:35], 0, v[156:157]
	s_mov_b32 m0, s61
	s_nop 0
	global_load_lds_dwordx4 v[188:189], off
	ds_read_b128 v[188:191], v178 offset:32768
	ds_read_b128 v[192:195], v178 offset:33792
	ds_read_b128 v[196:199], v178 offset:34816
	ds_read_b128 v[200:203], v178 offset:35840
	ds_read_b128 v[204:207], v178 offset:36864
	ds_read_b128 v[208:211], v178 offset:37888
	ds_read_b128 v[212:215], v178 offset:38912
	ds_read_b128 v[216:219], v178 offset:39936
	s_setprio 0
	s_waitcnt vmcnt(8)
	s_waitcnt lgkmcnt(0)
	s_barrier
	s_waitcnt lgkmcnt(0)
	v_mfma_f32_16x16x32_bf16 v[124:127], v[128:131], v[188:191], v[124:127]
	v_mfma_f32_16x16x32_bf16 v[124:127], v[132:135], v[192:195], v[124:127]
	v_mfma_f32_16x16x32_bf16 v[120:123], v[140:143], v[192:195], v[120:123]
	v_mfma_f32_16x16x32_bf16 v[120:123], v[136:139], v[188:191], v[120:123]
	v_mfma_f32_16x16x32_bf16 v[116:119], v[144:147], v[188:191], v[116:119]
	v_mfma_f32_16x16x32_bf16 v[116:119], v[148:151], v[192:195], v[116:119]
	v_mfma_f32_16x16x32_bf16 v[112:115], v[184:187], v[192:195], v[112:115]
	v_mfma_f32_16x16x32_bf16 v[112:115], v[180:183], v[188:191], v[112:115]
	v_mfma_f32_16x16x32_bf16 v[96:99], v[180:183], v[196:199], v[96:99]
	v_mfma_f32_16x16x32_bf16 v[96:99], v[184:187], v[200:203], v[96:99]
	v_mfma_f32_16x16x32_bf16 v[100:103], v[148:151], v[200:203], v[100:103]
	v_mfma_f32_16x16x32_bf16 v[100:103], v[144:147], v[196:199], v[100:103]
	v_mfma_f32_16x16x32_bf16 v[104:107], v[136:139], v[196:199], v[104:107]
	v_mfma_f32_16x16x32_bf16 v[104:107], v[140:143], v[200:203], v[104:107]
	v_mfma_f32_16x16x32_bf16 v[108:111], v[132:135], v[200:203], v[108:111]
	v_mfma_f32_16x16x32_bf16 v[108:111], v[128:131], v[196:199], v[108:111]
	v_mfma_f32_16x16x32_bf16 v[92:95], v[128:131], v[204:207], v[92:95]
	v_mfma_f32_16x16x32_bf16 v[92:95], v[132:135], v[208:211], v[92:95]
	v_mfma_f32_16x16x32_bf16 v[88:91], v[140:143], v[208:211], v[88:91]
	v_mfma_f32_16x16x32_bf16 v[88:91], v[136:139], v[204:207], v[88:91]
	v_mfma_f32_16x16x32_bf16 v[84:87], v[144:147], v[204:207], v[84:87]
	v_mfma_f32_16x16x32_bf16 v[84:87], v[148:151], v[208:211], v[84:87]
	v_mfma_f32_16x16x32_bf16 v[80:83], v[184:187], v[208:211], v[80:83]
	v_mfma_f32_16x16x32_bf16 v[80:83], v[180:183], v[204:207], v[80:83]
	v_mfma_f32_16x16x32_bf16 v[64:67], v[180:183], v[212:215], v[64:67]
	v_mfma_f32_16x16x32_bf16 v[64:67], v[184:187], v[216:219], v[64:67]
	v_mfma_f32_16x16x32_bf16 v[68:71], v[148:151], v[216:219], v[68:71]
	v_mfma_f32_16x16x32_bf16 v[68:71], v[144:147], v[212:215], v[68:71]
	v_mfma_f32_16x16x32_bf16 v[72:75], v[136:139], v[212:215], v[72:75]
	v_mfma_f32_16x16x32_bf16 v[72:75], v[140:143], v[216:219], v[72:75]
	v_mfma_f32_16x16x32_bf16 v[76:79], v[132:135], v[216:219], v[76:79]
	v_mfma_f32_16x16x32_bf16 v[76:79], v[128:131], v[212:215], v[76:79]
	s_barrier
	s_setprio 1
	s_add_i32 s34, s41, s33
	v_lshl_add_u64 v[172:173], v[172:173], 0, s[16:17]
	s_mov_b32 m0, s34
	s_nop 0
	global_load_lds_dwordx4 v[172:173], off
	s_add_i32 m0, s34, 0x2000
	s_add_u32 s30, s30, 0x100800
	v_lshl_add_u64 v[172:173], v[220:221], 0, s[16:17]
	s_addc_u32 s31, s31, 0
	s_add_i32 s34, s42, s33
	global_load_lds_dwordx4 v[172:173], off
	v_lshl_add_u64 v[172:173], s[30:31], 0, v[154:155]
	s_mov_b32 m0, s34
	s_nop 0
	global_load_lds_dwordx4 v[172:173], off
	v_lshl_add_u64 v[172:173], s[30:31], 0, v[158:159]
	s_add_i32 m0, s34, 0x2000
	s_nop 0
	global_load_lds_dwordx4 v[172:173], off
	v_lshl_add_u64 v[172:173], v[222:223], 0, s[18:19]
	s_mov_b32 m0, s63
	s_nop 0
	global_load_lds_dwordx4 v[172:173], off
	v_lshl_add_u64 v[172:173], v[224:225], 0, s[18:19]
	s_mov_b32 m0, s64
	s_nop 0
	global_load_lds_dwordx4 v[172:173], off
	ds_read_b128 v[188:191], v178 offset:49152
	ds_read_b128 v[192:195], v178 offset:50176
	ds_read_b128 v[196:199], v178 offset:51200
	ds_read_b128 v[200:203], v178 offset:52224
	ds_read_b128 v[204:207], v178 offset:53248
	ds_read_b128 v[208:211], v178 offset:54272
	ds_read_b128 v[212:215], v178 offset:55296
	ds_read_b128 v[216:219], v178 offset:56320
	s_setprio 0
	s_waitcnt vmcnt(8)
	s_waitcnt lgkmcnt(0)
	s_barrier
	s_waitcnt lgkmcnt(0)
	v_mfma_f32_16x16x32_bf16 v[60:63], v[128:131], v[188:191], v[60:63]
	v_mfma_f32_16x16x32_bf16 v[60:63], v[132:135], v[192:195], v[60:63]
	v_mfma_f32_16x16x32_bf16 v[56:59], v[140:143], v[192:195], v[56:59]
	v_mfma_f32_16x16x32_bf16 v[56:59], v[136:139], v[188:191], v[56:59]
	v_mfma_f32_16x16x32_bf16 v[52:55], v[144:147], v[188:191], v[52:55]
	v_mfma_f32_16x16x32_bf16 v[52:55], v[148:151], v[192:195], v[52:55]
	v_mfma_f32_16x16x32_bf16 v[48:51], v[184:187], v[192:195], v[48:51]
	v_mfma_f32_16x16x32_bf16 v[48:51], v[180:183], v[188:191], v[48:51]
	v_mfma_f32_16x16x32_bf16 v[32:35], v[180:183], v[196:199], v[32:35]
	v_mfma_f32_16x16x32_bf16 v[32:35], v[184:187], v[200:203], v[32:35]
	v_mfma_f32_16x16x32_bf16 v[36:39], v[148:151], v[200:203], v[36:39]
	v_mfma_f32_16x16x32_bf16 v[36:39], v[144:147], v[196:199], v[36:39]
	v_mfma_f32_16x16x32_bf16 v[40:43], v[136:139], v[196:199], v[40:43]
	v_mfma_f32_16x16x32_bf16 v[40:43], v[140:143], v[200:203], v[40:43]
	v_mfma_f32_16x16x32_bf16 v[44:47], v[132:135], v[200:203], v[44:47]
	v_mfma_f32_16x16x32_bf16 v[44:47], v[128:131], v[196:199], v[44:47]
	v_mfma_f32_16x16x32_bf16 v[28:31], v[128:131], v[204:207], v[28:31]
	v_mfma_f32_16x16x32_bf16 v[28:31], v[132:135], v[208:211], v[28:31]
	v_mfma_f32_16x16x32_bf16 v[24:27], v[140:143], v[208:211], v[24:27]
	v_mfma_f32_16x16x32_bf16 v[24:27], v[136:139], v[204:207], v[24:27]
	v_mfma_f32_16x16x32_bf16 v[20:23], v[144:147], v[204:207], v[20:23]
	v_mfma_f32_16x16x32_bf16 v[20:23], v[148:151], v[208:211], v[20:23]
	v_mfma_f32_16x16x32_bf16 v[16:19], v[184:187], v[208:211], v[16:19]
	v_mfma_f32_16x16x32_bf16 v[16:19], v[180:183], v[204:207], v[16:19]
	v_mfma_f32_16x16x32_bf16 v[0:3], v[180:183], v[212:215], v[0:3]
	v_mfma_f32_16x16x32_bf16 v[0:3], v[184:187], v[216:219], v[0:3]
	v_mfma_f32_16x16x32_bf16 v[4:7], v[148:151], v[216:219], v[4:7]
	v_mfma_f32_16x16x32_bf16 v[4:7], v[144:147], v[212:215], v[4:7]
	v_mfma_f32_16x16x32_bf16 v[8:11], v[136:139], v[212:215], v[8:11]
	v_mfma_f32_16x16x32_bf16 v[8:11], v[140:143], v[216:219], v[8:11]
	v_mfma_f32_16x16x32_bf16 v[12:15], v[132:135], v[216:219], v[12:15]
	v_mfma_f32_16x16x32_bf16 v[12:15], v[128:131], v[212:215], v[12:15]
	s_barrier
	s_setprio 1
	s_add_i32 s40, s40, 2
	s_add_u32 s38, s38, 0x1000
	s_addc_u32 s39, s39, 0
	s_add_u32 s28, s28, 0x100
	s_addc_u32 s29, s29, 0
	s_cmp_gt_u32 s40, 61
	s_cbranch_scc0 .LBB0_1202
	s_setprio 0
	s_and_b64 vcc, exec, s[10:11]
	s_cbranch_vccz .LBB0_1205
	s_barrier

.LBB0_1263:
	ds_read_b128 v[146:149], v152
	ds_read_b128 v[156:159], v152 offset:1024
	ds_read_b128 v[160:163], v152 offset:2048
	ds_read_b128 v[164:167], v152 offset:3072
	ds_read_b128 v[168:171], v153
	ds_read_b128 v[172:175], v153 offset:1024
	ds_read_b128 v[176:179], v153 offset:2048
	ds_read_b128 v[180:183], v153 offset:3072
	s_add_u32 s22, s20, 0x100
	s_addc_u32 s23, s21, 0
	s_cmp_eq_u32 s46, 12
	s_cselect_b32 s27, s5, s23
	s_cselect_b32 s26, s4, s22
	s_cselect_b32 s25, s19, s15
	s_cselect_b32 s24, s18, s6
	v_lshl_add_u64 v[184:185], s[20:21], 0, v[136:137]
	s_add_i32 m0, s17, 0xc000
	s_nop 0
	global_load_lds_dwordx4 v[184:185], off
	v_lshl_add_u64 v[184:185], s[20:21], 0, v[138:139]
	s_add_i32 m0, s17, 0xe000
	s_nop 0
	global_load_lds_dwordx4 v[184:185], off
	ds_read_b128 v[184:187], v154
	ds_read_b128 v[188:191], v154 offset:1024
	ds_read_b128 v[192:195], v154 offset:2048
	ds_read_b128 v[196:199], v154 offset:3072
	ds_read_b128 v[200:203], v154 offset:4096
	ds_read_b128 v[204:207], v154 offset:5120
	ds_read_b128 v[208:211], v154 offset:6144
	ds_read_b128 v[212:215], v154 offset:7168
	s_setprio 0
	s_waitcnt vmcnt(8)
	s_waitcnt lgkmcnt(0)
	s_barrier
	s_waitcnt lgkmcnt(0)
	v_mfma_f32_16x16x32_bf16 v[124:127], v[146:149], v[184:187], v[124:127]
	v_mfma_f32_16x16x32_bf16 v[124:127], v[156:159], v[188:191], v[124:127]
	v_mfma_f32_16x16x32_bf16 v[120:123], v[164:167], v[188:191], v[120:123]
	v_mfma_f32_16x16x32_bf16 v[120:123], v[160:163], v[184:187], v[120:123]
	v_mfma_f32_16x16x32_bf16 v[116:119], v[168:171], v[184:187], v[116:119]
	v_mfma_f32_16x16x32_bf16 v[116:119], v[172:175], v[188:191], v[116:119]
	v_mfma_f32_16x16x32_bf16 v[108:111], v[180:183], v[188:191], v[108:111]
	v_mfma_f32_16x16x32_bf16 v[108:111], v[176:179], v[184:187], v[108:111]
	v_mfma_f32_16x16x32_bf16 v[92:95], v[176:179], v[192:195], v[92:95]
	v_mfma_f32_16x16x32_bf16 v[92:95], v[180:183], v[196:199], v[92:95]
	v_mfma_f32_16x16x32_bf16 v[100:103], v[172:175], v[196:199], v[100:103]
	v_mfma_f32_16x16x32_bf16 v[100:103], v[168:171], v[192:195], v[100:103]
	v_mfma_f32_16x16x32_bf16 v[104:107], v[160:163], v[192:195], v[104:107]
	v_mfma_f32_16x16x32_bf16 v[104:107], v[164:167], v[196:199], v[104:107]
	v_mfma_f32_16x16x32_bf16 v[112:115], v[156:159], v[196:199], v[112:115]
	v_mfma_f32_16x16x32_bf16 v[112:115], v[146:149], v[192:195], v[112:115]
	v_mfma_f32_16x16x32_bf16 v[96:99], v[146:149], v[200:203], v[96:99]
	v_mfma_f32_16x16x32_bf16 v[96:99], v[156:159], v[204:207], v[96:99]
	v_mfma_f32_16x16x32_bf16 v[88:91], v[164:167], v[204:207], v[88:91]
	v_mfma_f32_16x16x32_bf16 v[88:91], v[160:163], v[200:203], v[88:91]
	v_mfma_f32_16x16x32_bf16 v[84:87], v[168:171], v[200:203], v[84:87]
	v_mfma_f32_16x16x32_bf16 v[84:87], v[172:175], v[204:207], v[84:87]
	v_mfma_f32_16x16x32_bf16 v[76:79], v[180:183], v[204:207], v[76:79]
	v_mfma_f32_16x16x32_bf16 v[76:79], v[176:179], v[200:203], v[76:79]
	v_mfma_f32_16x16x32_bf16 v[64:67], v[176:179], v[208:211], v[64:67]
	v_mfma_f32_16x16x32_bf16 v[64:67], v[180:183], v[212:215], v[64:67]
	v_mfma_f32_16x16x32_bf16 v[68:71], v[172:175], v[212:215], v[68:71]
	v_mfma_f32_16x16x32_bf16 v[68:71], v[168:171], v[208:211], v[68:71]
	v_mfma_f32_16x16x32_bf16 v[72:75], v[160:163], v[208:211], v[72:75]
	v_mfma_f32_16x16x32_bf16 v[72:75], v[164:167], v[212:215], v[72:75]
	v_mfma_f32_16x16x32_bf16 v[80:83], v[156:159], v[212:215], v[80:83]
	v_mfma_f32_16x16x32_bf16 v[80:83], v[146:149], v[208:211], v[80:83]
	s_barrier
	s_setprio 1
	s_add_i32 s20, s41, s33
	v_lshl_add_u64 v[216:217], s[24:25], 0, v[130:131]
	s_mov_b32 m0, s20
	v_lshl_add_u64 v[218:219], s[24:25], 0, v[134:135]
	global_load_lds_dwordx4 v[216:217], off
	s_add_i32 m0, s20, 0x2000
	s_add_u32 s20, s24, 0x200000
	s_addc_u32 s21, s25, 0
	s_add_i32 s47, s42, s33
	global_load_lds_dwordx4 v[218:219], off
	v_lshl_add_u64 v[184:185], s[20:21], 0, v[130:131]
	s_mov_b32 m0, s47
	v_lshl_add_u64 v[220:221], s[26:27], 0, v[128:129]
	global_load_lds_dwordx4 v[184:185], off
	v_lshl_add_u64 v[184:185], s[20:21], 0, v[134:135]
	s_add_i32 m0, s47, 0x2000
	v_lshl_add_u64 v[222:223], s[26:27], 0, v[132:133]
	global_load_lds_dwordx4 v[184:185], off
	s_mov_b32 m0, s17
	s_nop 0
	global_load_lds_dwordx4 v[220:221], off
	s_mov_b32 m0, s34
	s_nop 0
	global_load_lds_dwordx4 v[222:223], off
	ds_read_b128 v[184:187], v154 offset:16384
	ds_read_b128 v[188:191], v154 offset:17408
	ds_read_b128 v[192:195], v154 offset:18432
	ds_read_b128 v[196:199], v154 offset:19456
	ds_read_b128 v[200:203], v154 offset:20480
	ds_read_b128 v[204:207], v154 offset:21504
	ds_read_b128 v[208:211], v154 offset:22528
	ds_read_b128 v[212:215], v154 offset:23552
	s_setprio 0
	s_waitcnt vmcnt(8)
	s_waitcnt lgkmcnt(0)
	s_barrier
	s_waitcnt lgkmcnt(0)
	v_mfma_f32_16x16x32_bf16 v[60:63], v[146:149], v[184:187], v[60:63]
	v_mfma_f32_16x16x32_bf16 v[60:63], v[156:159], v[188:191], v[60:63]
	v_mfma_f32_16x16x32_bf16 v[56:59], v[164:167], v[188:191], v[56:59]
	v_mfma_f32_16x16x32_bf16 v[56:59], v[160:163], v[184:187], v[56:59]
	v_mfma_f32_16x16x32_bf16 v[52:55], v[168:171], v[184:187], v[52:55]
	v_mfma_f32_16x16x32_bf16 v[52:55], v[172:175], v[188:191], v[52:55]
	v_mfma_f32_16x16x32_bf16 v[44:47], v[180:183], v[188:191], v[44:47]
	v_mfma_f32_16x16x32_bf16 v[44:47], v[176:179], v[184:187], v[44:47]
	v_mfma_f32_16x16x32_bf16 v[28:31], v[176:179], v[192:195], v[28:31]
	v_mfma_f32_16x16x32_bf16 v[28:31], v[180:183], v[196:199], v[28:31]
	v_mfma_f32_16x16x32_bf16 v[36:39], v[172:175], v[196:199], v[36:39]
	v_mfma_f32_16x16x32_bf16 v[36:39], v[168:171], v[192:195], v[36:39]
	v_mfma_f32_16x16x32_bf16 v[40:43], v[160:163], v[192:195], v[40:43]
	v_mfma_f32_16x16x32_bf16 v[40:43], v[164:167], v[196:199], v[40:43]
	v_mfma_f32_16x16x32_bf16 v[48:51], v[156:159], v[196:199], v[48:51]
	v_mfma_f32_16x16x32_bf16 v[48:51], v[146:149], v[192:195], v[48:51]
	v_mfma_f32_16x16x32_bf16 v[32:35], v[146:149], v[200:203], v[32:35]
	v_mfma_f32_16x16x32_bf16 v[32:35], v[156:159], v[204:207], v[32:35]
	v_mfma_f32_16x16x32_bf16 v[24:27], v[164:167], v[204:207], v[24:27]
	v_mfma_f32_16x16x32_bf16 v[24:27], v[160:163], v[200:203], v[24:27]
	v_mfma_f32_16x16x32_bf16 v[20:23], v[168:171], v[200:203], v[20:23]
	v_mfma_f32_16x16x32_bf16 v[20:23], v[172:175], v[204:207], v[20:23]
	v_mfma_f32_16x16x32_bf16 v[12:15], v[180:183], v[204:207], v[12:15]
	v_mfma_f32_16x16x32_bf16 v[12:15], v[176:179], v[200:203], v[12:15]
	v_mfma_f32_16x16x32_bf16 v[0:3], v[176:179], v[208:211], v[0:3]
	v_mfma_f32_16x16x32_bf16 v[0:3], v[180:183], v[212:215], v[0:3]
	v_mfma_f32_16x16x32_bf16 v[4:7], v[172:175], v[212:215], v[4:7]
	v_mfma_f32_16x16x32_bf16 v[4:7], v[168:171], v[208:211], v[4:7]
	v_mfma_f32_16x16x32_bf16 v[8:11], v[160:163], v[208:211], v[8:11]
	v_mfma_f32_16x16x32_bf16 v[8:11], v[164:167], v[212:215], v[8:11]
	v_mfma_f32_16x16x32_bf16 v[16:19], v[156:159], v[212:215], v[16:19]
	v_mfma_f32_16x16x32_bf16 v[16:19], v[146:149], v[208:211], v[16:19]
	s_barrier
	s_setprio 1
	s_add_i32 s47, 0, 0x18000
	v_add_u32_e32 v144, s47, v145
	s_add_i32 s48, 0, 0x1c000
	ds_read_b128 v[146:149], v144
	ds_read_b128 v[156:159], v144 offset:1024
	ds_read_b128 v[160:163], v144 offset:2048
	ds_read_b128 v[164:167], v144 offset:3072
	v_add_u32_e32 v144, s48, v145
	ds_read_b128 v[168:171], v144
	ds_read_b128 v[172:175], v144 offset:1024
	ds_read_b128 v[176:179], v144 offset:2048
	ds_read_b128 v[180:183], v144 offset:3072
	s_add_u32 s20, s26, 0x200000
	s_addc_u32 s21, s27, 0
	s_mov_b32 m0, s35
	v_lshl_add_u64 v[184:185], s[20:21], 0, v[128:129]
	global_load_lds_dwordx4 v[184:185], off
	v_lshl_add_u64 v[184:185], s[20:21], 0, v[132:133]
	s_mov_b32 m0, s36
	s_nop 0
	global_load_lds_dwordx4 v[184:185], off
	ds_read_b128 v[184:187], v154 offset:32768
	ds_read_b128 v[188:191], v154 offset:33792
	ds_read_b128 v[192:195], v154 offset:34816
	ds_read_b128 v[196:199], v154 offset:35840
	ds_read_b128 v[200:203], v154 offset:36864
	ds_read_b128 v[204:207], v154 offset:37888
	ds_read_b128 v[208:211], v154 offset:38912
	ds_read_b128 v[212:215], v154 offset:39936
	s_setprio 0
	s_waitcnt vmcnt(8)
	s_waitcnt lgkmcnt(0)
	s_barrier
	s_waitcnt lgkmcnt(0)
	v_mfma_f32_16x16x32_bf16 v[124:127], v[146:149], v[184:187], v[124:127]
	v_mfma_f32_16x16x32_bf16 v[124:127], v[156:159], v[188:191], v[124:127]
	v_mfma_f32_16x16x32_bf16 v[120:123], v[164:167], v[188:191], v[120:123]
	v_mfma_f32_16x16x32_bf16 v[120:123], v[160:163], v[184:187], v[120:123]
	v_mfma_f32_16x16x32_bf16 v[116:119], v[168:171], v[184:187], v[116:119]
	v_mfma_f32_16x16x32_bf16 v[116:119], v[172:175], v[188:191], v[116:119]
	v_mfma_f32_16x16x32_bf16 v[108:111], v[180:183], v[188:191], v[108:111]
	v_mfma_f32_16x16x32_bf16 v[108:111], v[176:179], v[184:187], v[108:111]
	v_mfma_f32_16x16x32_bf16 v[92:95], v[176:179], v[192:195], v[92:95]
	v_mfma_f32_16x16x32_bf16 v[92:95], v[180:183], v[196:199], v[92:95]
	v_mfma_f32_16x16x32_bf16 v[100:103], v[172:175], v[196:199], v[100:103]
	v_mfma_f32_16x16x32_bf16 v[100:103], v[168:171], v[192:195], v[100:103]
	v_mfma_f32_16x16x32_bf16 v[104:107], v[160:163], v[192:195], v[104:107]
	v_mfma_f32_16x16x32_bf16 v[104:107], v[164:167], v[196:199], v[104:107]
	v_mfma_f32_16x16x32_bf16 v[112:115], v[156:159], v[196:199], v[112:115]
	v_mfma_f32_16x16x32_bf16 v[112:115], v[146:149], v[192:195], v[112:115]
	v_mfma_f32_16x16x32_bf16 v[96:99], v[146:149], v[200:203], v[96:99]
	v_mfma_f32_16x16x32_bf16 v[96:99], v[156:159], v[204:207], v[96:99]
	v_mfma_f32_16x16x32_bf16 v[88:91], v[164:167], v[204:207], v[88:91]
	v_mfma_f32_16x16x32_bf16 v[88:91], v[160:163], v[200:203], v[88:91]
	v_mfma_f32_16x16x32_bf16 v[84:87], v[168:171], v[200:203], v[84:87]
	v_mfma_f32_16x16x32_bf16 v[84:87], v[172:175], v[204:207], v[84:87]
	v_mfma_f32_16x16x32_bf16 v[76:79], v[180:183], v[204:207], v[76:79]
	v_mfma_f32_16x16x32_bf16 v[76:79], v[176:179], v[200:203], v[76:79]
	v_mfma_f32_16x16x32_bf16 v[64:67], v[176:179], v[208:211], v[64:67]
	v_mfma_f32_16x16x32_bf16 v[64:67], v[180:183], v[212:215], v[64:67]
	v_mfma_f32_16x16x32_bf16 v[68:71], v[172:175], v[212:215], v[68:71]
	v_mfma_f32_16x16x32_bf16 v[68:71], v[168:171], v[208:211], v[68:71]
	v_mfma_f32_16x16x32_bf16 v[72:75], v[160:163], v[208:211], v[72:75]
	v_mfma_f32_16x16x32_bf16 v[72:75], v[164:167], v[212:215], v[72:75]
	v_mfma_f32_16x16x32_bf16 v[80:83], v[156:159], v[212:215], v[80:83]
	v_mfma_f32_16x16x32_bf16 v[80:83], v[146:149], v[208:211], v[80:83]
	s_barrier
	s_setprio 1
	s_add_i32 s20, s47, s33
	v_lshl_add_u64 v[184:185], v[216:217], 0, s[12:13]
	s_mov_b32 m0, s20
	s_nop 0
	global_load_lds_dwordx4 v[184:185], off
	s_add_i32 m0, s20, 0x2000
	s_add_u32 s20, s24, 0x200080
	v_lshl_add_u64 v[184:185], v[218:219], 0, s[12:13]
	s_addc_u32 s21, s25, 0
	s_add_i32 s24, s48, s33
	global_load_lds_dwordx4 v[184:185], off
	v_lshl_add_u64 v[184:185], s[20:21], 0, v[130:131]
	s_mov_b32 m0, s24
	s_nop 0
	global_load_lds_dwordx4 v[184:185], off
	v_lshl_add_u64 v[184:185], s[20:21], 0, v[134:135]
	s_add_i32 m0, s24, 0x2000
	s_nop 0
	global_load_lds_dwordx4 v[184:185], off
	v_lshl_add_u64 v[184:185], v[220:221], 0, s[12:13]
	s_mov_b32 m0, s37
	s_nop 0
	global_load_lds_dwordx4 v[184:185], off
	v_lshl_add_u64 v[184:185], v[222:223], 0, s[12:13]
	s_mov_b32 m0, s38
	s_nop 0
	global_load_lds_dwordx4 v[184:185], off
	ds_read_b128 v[184:187], v154 offset:49152
	ds_read_b128 v[188:191], v154 offset:50176
	ds_read_b128 v[192:195], v154 offset:51200
	ds_read_b128 v[196:199], v154 offset:52224
	ds_read_b128 v[200:203], v154 offset:53248
	ds_read_b128 v[204:207], v154 offset:54272
	ds_read_b128 v[208:211], v154 offset:55296
	ds_read_b128 v[212:215], v154 offset:56320
	s_setprio 0
	s_waitcnt vmcnt(8)
	s_waitcnt lgkmcnt(0)
	s_barrier
	s_waitcnt lgkmcnt(0)
	v_mfma_f32_16x16x32_bf16 v[60:63], v[146:149], v[184:187], v[60:63]
	v_mfma_f32_16x16x32_bf16 v[60:63], v[156:159], v[188:191], v[60:63]
	v_mfma_f32_16x16x32_bf16 v[56:59], v[164:167], v[188:191], v[56:59]
	v_mfma_f32_16x16x32_bf16 v[56:59], v[160:163], v[184:187], v[56:59]
	v_mfma_f32_16x16x32_bf16 v[52:55], v[168:171], v[184:187], v[52:55]
	v_mfma_f32_16x16x32_bf16 v[52:55], v[172:175], v[188:191], v[52:55]
	v_mfma_f32_16x16x32_bf16 v[44:47], v[180:183], v[188:191], v[44:47]
	v_mfma_f32_16x16x32_bf16 v[44:47], v[176:179], v[184:187], v[44:47]
	v_mfma_f32_16x16x32_bf16 v[28:31], v[176:179], v[192:195], v[28:31]
	v_mfma_f32_16x16x32_bf16 v[28:31], v[180:183], v[196:199], v[28:31]
	v_mfma_f32_16x16x32_bf16 v[36:39], v[172:175], v[196:199], v[36:39]
	v_mfma_f32_16x16x32_bf16 v[36:39], v[168:171], v[192:195], v[36:39]
	v_mfma_f32_16x16x32_bf16 v[40:43], v[160:163], v[192:195], v[40:43]
	v_mfma_f32_16x16x32_bf16 v[40:43], v[164:167], v[196:199], v[40:43]
	v_mfma_f32_16x16x32_bf16 v[48:51], v[156:159], v[196:199], v[48:51]
	v_mfma_f32_16x16x32_bf16 v[48:51], v[146:149], v[192:195], v[48:51]
	v_mfma_f32_16x16x32_bf16 v[32:35], v[146:149], v[200:203], v[32:35]
	v_mfma_f32_16x16x32_bf16 v[32:35], v[156:159], v[204:207], v[32:35]
	v_mfma_f32_16x16x32_bf16 v[24:27], v[164:167], v[204:207], v[24:27]
	v_mfma_f32_16x16x32_bf16 v[24:27], v[160:163], v[200:203], v[24:27]
	v_mfma_f32_16x16x32_bf16 v[20:23], v[168:171], v[200:203], v[20:23]
	v_mfma_f32_16x16x32_bf16 v[20:23], v[172:175], v[204:207], v[20:23]
	v_mfma_f32_16x16x32_bf16 v[12:15], v[180:183], v[204:207], v[12:15]
	v_mfma_f32_16x16x32_bf16 v[12:15], v[176:179], v[200:203], v[12:15]
	v_mfma_f32_16x16x32_bf16 v[0:3], v[176:179], v[208:211], v[0:3]
	v_mfma_f32_16x16x32_bf16 v[0:3], v[180:183], v[212:215], v[0:3]
	v_mfma_f32_16x16x32_bf16 v[4:7], v[172:175], v[212:215], v[4:7]
	v_mfma_f32_16x16x32_bf16 v[4:7], v[168:171], v[208:211], v[4:7]
	v_mfma_f32_16x16x32_bf16 v[8:11], v[160:163], v[208:211], v[8:11]
	v_mfma_f32_16x16x32_bf16 v[8:11], v[164:167], v[212:215], v[8:11]
	v_mfma_f32_16x16x32_bf16 v[16:19], v[156:159], v[212:215], v[16:19]
	v_mfma_f32_16x16x32_bf16 v[16:19], v[146:149], v[208:211], v[16:19]
	s_barrier
	s_setprio 1
	s_add_i32 s46, s46, 2
	s_add_u32 s6, s6, 0x100
	s_addc_u32 s15, s15, 0
	s_cmp_gt_u32 s46, 13
	s_mov_b64 s[20:21], s[22:23]
	s_cbranch_scc0 .LBB0_1263
	s_setprio 0
	s_and_b64 vcc, exec, s[8:9]
	s_cbranch_vccz .LBB0_1266
	s_barrier

.LBB0_1340:
	v_add_u32_e32 v166, s51, v152
	v_add_u32_e32 v182, s52, v152
	ds_read_b128 v[154:157], v166
	ds_read_b128 v[158:161], v166 offset:1024
	ds_read_b128 v[162:165], v166 offset:2048
	ds_read_b128 v[166:169], v166 offset:3072
	ds_read_b128 v[170:173], v182
	ds_read_b128 v[174:177], v182 offset:1024
	ds_read_b128 v[178:181], v182 offset:2048
	ds_read_b128 v[182:185], v182 offset:3072
	s_add_u32 s30, s10, s28
	s_addc_u32 s31, s11, s29
	s_cmp_eq_u32 s58, 60
	s_cselect_b32 s35, s23, s31
	s_cselect_b32 s34, s54, s30
	s_cselect_b32 s31, s21, s57
	s_cselect_b32 s30, s55, s56
	v_lshl_add_u64 v[186:187], s[10:11], 0, v[146:147]
	s_add_i32 m0, s44, 0xc000
	s_nop 0
	global_load_lds_dwordx4 v[186:187], off
	v_lshl_add_u64 v[186:187], s[10:11], 0, v[144:145]
	s_add_i32 m0, s44, 0xe000
	s_nop 0
	global_load_lds_dwordx4 v[186:187], off
	ds_read_b128 v[186:189], v153
	ds_read_b128 v[190:193], v153 offset:1024
	ds_read_b128 v[194:197], v153 offset:2048
	ds_read_b128 v[198:201], v153 offset:3072
	ds_read_b128 v[202:205], v153 offset:4096
	ds_read_b128 v[206:209], v153 offset:5120
	ds_read_b128 v[210:213], v153 offset:6144
	ds_read_b128 v[214:217], v153 offset:7168
	s_setprio 0
	s_waitcnt vmcnt(8)
	s_waitcnt lgkmcnt(0)
	s_barrier
	s_waitcnt lgkmcnt(0)
	v_mfma_f32_16x16x32_bf16 v[124:127], v[154:157], v[186:189], v[124:127]
	v_mfma_f32_16x16x32_bf16 v[124:127], v[158:161], v[190:193], v[124:127]
	v_mfma_f32_16x16x32_bf16 v[120:123], v[166:169], v[190:193], v[120:123]
	v_mfma_f32_16x16x32_bf16 v[120:123], v[162:165], v[186:189], v[120:123]
	v_mfma_f32_16x16x32_bf16 v[116:119], v[170:173], v[186:189], v[116:119]
	v_mfma_f32_16x16x32_bf16 v[116:119], v[174:177], v[190:193], v[116:119]
	v_mfma_f32_16x16x32_bf16 v[112:115], v[182:185], v[190:193], v[112:115]
	v_mfma_f32_16x16x32_bf16 v[112:115], v[178:181], v[186:189], v[112:115]
	v_mfma_f32_16x16x32_bf16 v[96:99], v[178:181], v[194:197], v[96:99]
	v_mfma_f32_16x16x32_bf16 v[96:99], v[182:185], v[198:201], v[96:99]
	v_mfma_f32_16x16x32_bf16 v[100:103], v[174:177], v[198:201], v[100:103]
	v_mfma_f32_16x16x32_bf16 v[100:103], v[170:173], v[194:197], v[100:103]
	v_mfma_f32_16x16x32_bf16 v[104:107], v[162:165], v[194:197], v[104:107]
	v_mfma_f32_16x16x32_bf16 v[104:107], v[166:169], v[198:201], v[104:107]
	v_mfma_f32_16x16x32_bf16 v[108:111], v[158:161], v[198:201], v[108:111]
	v_mfma_f32_16x16x32_bf16 v[108:111], v[154:157], v[194:197], v[108:111]
	v_mfma_f32_16x16x32_bf16 v[92:95], v[154:157], v[202:205], v[92:95]
	v_mfma_f32_16x16x32_bf16 v[92:95], v[158:161], v[206:209], v[92:95]
	v_mfma_f32_16x16x32_bf16 v[88:91], v[166:169], v[206:209], v[88:91]
	v_mfma_f32_16x16x32_bf16 v[88:91], v[162:165], v[202:205], v[88:91]
	v_mfma_f32_16x16x32_bf16 v[84:87], v[170:173], v[202:205], v[84:87]
	v_mfma_f32_16x16x32_bf16 v[84:87], v[174:177], v[206:209], v[84:87]
	v_mfma_f32_16x16x32_bf16 v[80:83], v[182:185], v[206:209], v[80:83]
	v_mfma_f32_16x16x32_bf16 v[80:83], v[178:181], v[202:205], v[80:83]
	v_mfma_f32_16x16x32_bf16 v[64:67], v[178:181], v[210:213], v[64:67]
	v_mfma_f32_16x16x32_bf16 v[64:67], v[182:185], v[214:217], v[64:67]
	v_mfma_f32_16x16x32_bf16 v[68:71], v[174:177], v[214:217], v[68:71]
	v_mfma_f32_16x16x32_bf16 v[68:71], v[170:173], v[210:213], v[68:71]
	v_mfma_f32_16x16x32_bf16 v[72:75], v[162:165], v[210:213], v[72:75]
	v_mfma_f32_16x16x32_bf16 v[72:75], v[166:169], v[214:217], v[72:75]
	v_mfma_f32_16x16x32_bf16 v[76:79], v[158:161], v[214:217], v[76:79]
	v_mfma_f32_16x16x32_bf16 v[76:79], v[154:157], v[210:213], v[76:79]
	s_barrier
	s_setprio 1
	s_add_i32 s59, s51, s43
	v_lshl_add_u64 v[218:219], s[30:31], 0, v[130:131]
	s_mov_b32 m0, s59
	v_lshl_add_u64 v[220:221], s[30:31], 0, v[134:135]
	global_load_lds_dwordx4 v[218:219], off
	s_add_i32 m0, s59, 0x2000
	s_add_u32 s60, s30, 0x100000
	s_addc_u32 s61, s31, 0
	s_add_i32 s59, s52, s43
	global_load_lds_dwordx4 v[220:221], off
	v_lshl_add_u64 v[186:187], s[60:61], 0, v[130:131]
	s_mov_b32 m0, s59
	v_lshl_add_u64 v[222:223], s[34:35], 0, v[128:129]
	global_load_lds_dwordx4 v[186:187], off
	v_lshl_add_u64 v[186:187], s[60:61], 0, v[134:135]
	s_add_i32 m0, s59, 0x2000
	v_lshl_add_u64 v[224:225], s[34:35], 0, v[132:133]
	global_load_lds_dwordx4 v[186:187], off
	s_mov_b32 m0, s44
	s_nop 0
	global_load_lds_dwordx4 v[222:223], off
	s_mov_b32 m0, s45
	s_nop 0
	global_load_lds_dwordx4 v[224:225], off
	ds_read_b128 v[186:189], v153 offset:16384
	ds_read_b128 v[190:193], v153 offset:17408
	ds_read_b128 v[194:197], v153 offset:18432
	ds_read_b128 v[198:201], v153 offset:19456
	ds_read_b128 v[202:205], v153 offset:20480
	ds_read_b128 v[206:209], v153 offset:21504
	ds_read_b128 v[210:213], v153 offset:22528
	ds_read_b128 v[214:217], v153 offset:23552
	s_setprio 0
	s_waitcnt vmcnt(8)
	s_waitcnt lgkmcnt(0)
	s_barrier
	s_waitcnt lgkmcnt(0)
	v_mfma_f32_16x16x32_bf16 v[60:63], v[154:157], v[186:189], v[60:63]
	v_mfma_f32_16x16x32_bf16 v[60:63], v[158:161], v[190:193], v[60:63]
	v_mfma_f32_16x16x32_bf16 v[56:59], v[166:169], v[190:193], v[56:59]
	v_mfma_f32_16x16x32_bf16 v[56:59], v[162:165], v[186:189], v[56:59]
	v_mfma_f32_16x16x32_bf16 v[52:55], v[170:173], v[186:189], v[52:55]
	v_mfma_f32_16x16x32_bf16 v[52:55], v[174:177], v[190:193], v[52:55]
	v_mfma_f32_16x16x32_bf16 v[48:51], v[182:185], v[190:193], v[48:51]
	v_mfma_f32_16x16x32_bf16 v[48:51], v[178:181], v[186:189], v[48:51]
	v_mfma_f32_16x16x32_bf16 v[32:35], v[178:181], v[194:197], v[32:35]
	v_mfma_f32_16x16x32_bf16 v[32:35], v[182:185], v[198:201], v[32:35]
	v_mfma_f32_16x16x32_bf16 v[36:39], v[174:177], v[198:201], v[36:39]
	v_mfma_f32_16x16x32_bf16 v[36:39], v[170:173], v[194:197], v[36:39]
	v_mfma_f32_16x16x32_bf16 v[40:43], v[162:165], v[194:197], v[40:43]
	v_mfma_f32_16x16x32_bf16 v[40:43], v[166:169], v[198:201], v[40:43]
	v_mfma_f32_16x16x32_bf16 v[44:47], v[158:161], v[198:201], v[44:47]
	v_mfma_f32_16x16x32_bf16 v[44:47], v[154:157], v[194:197], v[44:47]
	v_mfma_f32_16x16x32_bf16 v[28:31], v[154:157], v[202:205], v[28:31]
	v_mfma_f32_16x16x32_bf16 v[28:31], v[158:161], v[206:209], v[28:31]
	v_mfma_f32_16x16x32_bf16 v[24:27], v[166:169], v[206:209], v[24:27]
	v_mfma_f32_16x16x32_bf16 v[24:27], v[162:165], v[202:205], v[24:27]
	v_mfma_f32_16x16x32_bf16 v[20:23], v[170:173], v[202:205], v[20:23]
	v_mfma_f32_16x16x32_bf16 v[20:23], v[174:177], v[206:209], v[20:23]
	v_mfma_f32_16x16x32_bf16 v[16:19], v[182:185], v[206:209], v[16:19]
	v_mfma_f32_16x16x32_bf16 v[16:19], v[178:181], v[202:205], v[16:19]
	v_mfma_f32_16x16x32_bf16 v[0:3], v[178:181], v[210:213], v[0:3]
	v_mfma_f32_16x16x32_bf16 v[0:3], v[182:185], v[214:217], v[0:3]
	v_mfma_f32_16x16x32_bf16 v[4:7], v[174:177], v[214:217], v[4:7]
	v_mfma_f32_16x16x32_bf16 v[4:7], v[170:173], v[210:213], v[4:7]
	v_mfma_f32_16x16x32_bf16 v[8:11], v[162:165], v[210:213], v[8:11]
	v_mfma_f32_16x16x32_bf16 v[8:11], v[166:169], v[214:217], v[8:11]
	v_mfma_f32_16x16x32_bf16 v[12:15], v[158:161], v[214:217], v[12:15]
	v_mfma_f32_16x16x32_bf16 v[12:15], v[154:157], v[210:213], v[12:15]
	s_barrier
	s_setprio 1
	s_add_i32 s59, 0, 0x18000
	s_add_i32 s60, 0, 0x1c000
	v_add_u32_e32 v166, s59, v152
	v_add_u32_e32 v182, s60, v152
	ds_read_b128 v[154:157], v166
	ds_read_b128 v[158:161], v166 offset:1024
	ds_read_b128 v[162:165], v166 offset:2048
	ds_read_b128 v[166:169], v166 offset:3072
	ds_read_b128 v[170:173], v182
	ds_read_b128 v[174:177], v182 offset:1024
	ds_read_b128 v[178:181], v182 offset:2048
	ds_read_b128 v[182:185], v182 offset:3072
	s_add_u32 s34, s34, 0x100000
	s_addc_u32 s35, s35, 0
	s_mov_b32 m0, s46
	v_lshl_add_u64 v[186:187], s[34:35], 0, v[128:129]
	global_load_lds_dwordx4 v[186:187], off
	v_lshl_add_u64 v[186:187], s[34:35], 0, v[132:133]
	s_mov_b32 m0, s47
	s_nop 0
	global_load_lds_dwordx4 v[186:187], off
	ds_read_b128 v[186:189], v153 offset:32768
	ds_read_b128 v[190:193], v153 offset:33792
	ds_read_b128 v[194:197], v153 offset:34816
	ds_read_b128 v[198:201], v153 offset:35840
	ds_read_b128 v[202:205], v153 offset:36864
	ds_read_b128 v[206:209], v153 offset:37888
	ds_read_b128 v[210:213], v153 offset:38912
	ds_read_b128 v[214:217], v153 offset:39936
	s_setprio 0
	s_waitcnt vmcnt(8)
	s_waitcnt lgkmcnt(0)
	s_barrier
	s_waitcnt lgkmcnt(0)
	v_mfma_f32_16x16x32_bf16 v[124:127], v[154:157], v[186:189], v[124:127]
	v_mfma_f32_16x16x32_bf16 v[124:127], v[158:161], v[190:193], v[124:127]
	v_mfma_f32_16x16x32_bf16 v[120:123], v[166:169], v[190:193], v[120:123]
	v_mfma_f32_16x16x32_bf16 v[120:123], v[162:165], v[186:189], v[120:123]
	v_mfma_f32_16x16x32_bf16 v[116:119], v[170:173], v[186:189], v[116:119]
	v_mfma_f32_16x16x32_bf16 v[116:119], v[174:177], v[190:193], v[116:119]
	v_mfma_f32_16x16x32_bf16 v[112:115], v[182:185], v[190:193], v[112:115]
	v_mfma_f32_16x16x32_bf16 v[112:115], v[178:181], v[186:189], v[112:115]
	v_mfma_f32_16x16x32_bf16 v[96:99], v[178:181], v[194:197], v[96:99]
	v_mfma_f32_16x16x32_bf16 v[96:99], v[182:185], v[198:201], v[96:99]
	v_mfma_f32_16x16x32_bf16 v[100:103], v[174:177], v[198:201], v[100:103]
	v_mfma_f32_16x16x32_bf16 v[100:103], v[170:173], v[194:197], v[100:103]
	v_mfma_f32_16x16x32_bf16 v[104:107], v[162:165], v[194:197], v[104:107]
	v_mfma_f32_16x16x32_bf16 v[104:107], v[166:169], v[198:201], v[104:107]
	v_mfma_f32_16x16x32_bf16 v[108:111], v[158:161], v[198:201], v[108:111]
	v_mfma_f32_16x16x32_bf16 v[108:111], v[154:157], v[194:197], v[108:111]
	v_mfma_f32_16x16x32_bf16 v[92:95], v[154:157], v[202:205], v[92:95]
	v_mfma_f32_16x16x32_bf16 v[92:95], v[158:161], v[206:209], v[92:95]
	v_mfma_f32_16x16x32_bf16 v[88:91], v[166:169], v[206:209], v[88:91]
	v_mfma_f32_16x16x32_bf16 v[88:91], v[162:165], v[202:205], v[88:91]
	v_mfma_f32_16x16x32_bf16 v[84:87], v[170:173], v[202:205], v[84:87]
	v_mfma_f32_16x16x32_bf16 v[84:87], v[174:177], v[206:209], v[84:87]
	v_mfma_f32_16x16x32_bf16 v[80:83], v[182:185], v[206:209], v[80:83]
	v_mfma_f32_16x16x32_bf16 v[80:83], v[178:181], v[202:205], v[80:83]
	v_mfma_f32_16x16x32_bf16 v[64:67], v[178:181], v[210:213], v[64:67]
	v_mfma_f32_16x16x32_bf16 v[64:67], v[182:185], v[214:217], v[64:67]
	v_mfma_f32_16x16x32_bf16 v[68:71], v[174:177], v[214:217], v[68:71]
	v_mfma_f32_16x16x32_bf16 v[68:71], v[170:173], v[210:213], v[68:71]
	v_mfma_f32_16x16x32_bf16 v[72:75], v[162:165], v[210:213], v[72:75]
	v_mfma_f32_16x16x32_bf16 v[72:75], v[166:169], v[214:217], v[72:75]
	v_mfma_f32_16x16x32_bf16 v[76:79], v[158:161], v[214:217], v[76:79]
	v_mfma_f32_16x16x32_bf16 v[76:79], v[154:157], v[210:213], v[76:79]
	s_barrier
	s_setprio 1
	s_add_i32 s34, s59, s43
	v_lshl_add_u64 v[186:187], v[218:219], 0, s[14:15]
	s_mov_b32 m0, s34
	s_nop 0
	global_load_lds_dwordx4 v[186:187], off
	s_add_i32 m0, s34, 0x2000
	s_add_u32 s30, s30, 0x100080
	v_lshl_add_u64 v[186:187], v[220:221], 0, s[14:15]
	s_addc_u32 s31, s31, 0
	s_add_i32 s34, s60, s43
	global_load_lds_dwordx4 v[186:187], off
	v_lshl_add_u64 v[186:187], s[30:31], 0, v[130:131]
	s_mov_b32 m0, s34
	s_nop 0
	global_load_lds_dwordx4 v[186:187], off
	v_lshl_add_u64 v[186:187], s[30:31], 0, v[134:135]
	s_add_i32 m0, s34, 0x2000
	s_nop 0
	global_load_lds_dwordx4 v[186:187], off
	v_lshl_add_u64 v[186:187], v[222:223], 0, s[16:17]
	s_mov_b32 m0, s49
	s_nop 0
	global_load_lds_dwordx4 v[186:187], off
	v_lshl_add_u64 v[186:187], v[224:225], 0, s[16:17]
	s_mov_b32 m0, s50
	s_nop 0
	global_load_lds_dwordx4 v[186:187], off
	ds_read_b128 v[186:189], v153 offset:49152
	ds_read_b128 v[190:193], v153 offset:50176
	ds_read_b128 v[194:197], v153 offset:51200
	ds_read_b128 v[198:201], v153 offset:52224
	ds_read_b128 v[202:205], v153 offset:53248
	ds_read_b128 v[206:209], v153 offset:54272
	ds_read_b128 v[210:213], v153 offset:55296
	ds_read_b128 v[214:217], v153 offset:56320
	s_setprio 0
	s_waitcnt vmcnt(8)
	s_waitcnt lgkmcnt(0)
	s_barrier
	s_waitcnt lgkmcnt(0)
	v_mfma_f32_16x16x32_bf16 v[60:63], v[154:157], v[186:189], v[60:63]
	v_mfma_f32_16x16x32_bf16 v[60:63], v[158:161], v[190:193], v[60:63]
	v_mfma_f32_16x16x32_bf16 v[56:59], v[166:169], v[190:193], v[56:59]
	v_mfma_f32_16x16x32_bf16 v[56:59], v[162:165], v[186:189], v[56:59]
	v_mfma_f32_16x16x32_bf16 v[52:55], v[170:173], v[186:189], v[52:55]
	v_mfma_f32_16x16x32_bf16 v[52:55], v[174:177], v[190:193], v[52:55]
	v_mfma_f32_16x16x32_bf16 v[48:51], v[182:185], v[190:193], v[48:51]
	v_mfma_f32_16x16x32_bf16 v[48:51], v[178:181], v[186:189], v[48:51]
	v_mfma_f32_16x16x32_bf16 v[32:35], v[178:181], v[194:197], v[32:35]
	v_mfma_f32_16x16x32_bf16 v[32:35], v[182:185], v[198:201], v[32:35]
	v_mfma_f32_16x16x32_bf16 v[36:39], v[174:177], v[198:201], v[36:39]
	v_mfma_f32_16x16x32_bf16 v[36:39], v[170:173], v[194:197], v[36:39]
	v_mfma_f32_16x16x32_bf16 v[40:43], v[162:165], v[194:197], v[40:43]
	v_mfma_f32_16x16x32_bf16 v[40:43], v[166:169], v[198:201], v[40:43]
	v_mfma_f32_16x16x32_bf16 v[44:47], v[158:161], v[198:201], v[44:47]
	v_mfma_f32_16x16x32_bf16 v[44:47], v[154:157], v[194:197], v[44:47]
	v_mfma_f32_16x16x32_bf16 v[28:31], v[154:157], v[202:205], v[28:31]
	v_mfma_f32_16x16x32_bf16 v[28:31], v[158:161], v[206:209], v[28:31]
	v_mfma_f32_16x16x32_bf16 v[24:27], v[166:169], v[206:209], v[24:27]
	v_mfma_f32_16x16x32_bf16 v[24:27], v[162:165], v[202:205], v[24:27]
	v_mfma_f32_16x16x32_bf16 v[20:23], v[170:173], v[202:205], v[20:23]
	v_mfma_f32_16x16x32_bf16 v[20:23], v[174:177], v[206:209], v[20:23]
	v_mfma_f32_16x16x32_bf16 v[16:19], v[182:185], v[206:209], v[16:19]
	v_mfma_f32_16x16x32_bf16 v[16:19], v[178:181], v[202:205], v[16:19]
	v_mfma_f32_16x16x32_bf16 v[0:3], v[178:181], v[210:213], v[0:3]
	v_mfma_f32_16x16x32_bf16 v[0:3], v[182:185], v[214:217], v[0:3]
	v_mfma_f32_16x16x32_bf16 v[4:7], v[174:177], v[214:217], v[4:7]
	v_mfma_f32_16x16x32_bf16 v[4:7], v[170:173], v[210:213], v[4:7]
	v_mfma_f32_16x16x32_bf16 v[8:11], v[162:165], v[210:213], v[8:11]
	v_mfma_f32_16x16x32_bf16 v[8:11], v[166:169], v[214:217], v[8:11]
	v_mfma_f32_16x16x32_bf16 v[12:15], v[158:161], v[214:217], v[12:15]
	v_mfma_f32_16x16x32_bf16 v[12:15], v[154:157], v[210:213], v[12:15]
	s_barrier
	s_setprio 1
	s_add_i32 s58, s58, 2
	s_add_u32 s56, s56, 0x100
	s_addc_u32 s57, s57, 0
	s_add_u32 s28, s28, 0x1000
	s_addc_u32 s29, s29, 0
	v_lshl_add_u64 v[146:147], v[146:147], 0, s[18:19]
	s_cmp_gt_u32 s58, 61
	v_lshl_add_u64 v[144:145], v[144:145], 0, s[18:19]
	s_cbranch_scc0 .LBB0_1340
	s_setprio 0
	s_andn2_b64 vcc, exec, s[4:5]
	s_cbranch_vccnz .LBB0_1332
	v_mov_b32_e32 v0, 0
	s_mov_b32 s7, s20
	s_mov_b32 s6, s22
	s_mov_b64 s[8:9], s[26:27]
	s_mov_b64 s[10:11], s[24:25]
	s_mov_b32 s48, s53
	v_mov_b32_e32 v1, v0
	v_mov_b32_e32 v2, v0
	v_mov_b32_e32 v3, v0
	v_mov_b32_e32 v4, v0
	v_mov_b32_e32 v5, v0
	v_mov_b32_e32 v6, v0
	v_mov_b32_e32 v7, v0
	v_mov_b32_e32 v16, v0
	v_mov_b32_e32 v17, v0
	v_mov_b32_e32 v18, v0
	v_mov_b32_e32 v19, v0
	v_mov_b32_e32 v20, v0
	v_mov_b32_e32 v21, v0
	v_mov_b32_e32 v22, v0
	v_mov_b32_e32 v23, v0
	v_mov_b32_e32 v32, v0
	v_mov_b32_e32 v33, v0
	v_mov_b32_e32 v34, v0
	v_mov_b32_e32 v35, v0
	v_mov_b32_e32 v36, v0
	v_mov_b32_e32 v37, v0
	v_mov_b32_e32 v38, v0
	v_mov_b32_e32 v39, v0
	v_mov_b32_e32 v48, v0
	v_mov_b32_e32 v49, v0
	v_mov_b32_e32 v50, v0
	v_mov_b32_e32 v51, v0
	v_mov_b32_e32 v52, v0
	v_mov_b32_e32 v53, v0
	v_mov_b32_e32 v54, v0
	v_mov_b32_e32 v55, v0
	v_mov_b32_e32 v8, v0
	v_mov_b32_e32 v9, v0
	v_mov_b32_e32 v10, v0
	v_mov_b32_e32 v11, v0
	v_mov_b32_e32 v12, v0
	v_mov_b32_e32 v13, v0
	v_mov_b32_e32 v14, v0
	v_mov_b32_e32 v15, v0
	v_mov_b32_e32 v24, v0
	v_mov_b32_e32 v25, v0
	v_mov_b32_e32 v26, v0
	v_mov_b32_e32 v27, v0
	v_mov_b32_e32 v28, v0
	v_mov_b32_e32 v29, v0
	v_mov_b32_e32 v30, v0
	v_mov_b32_e32 v31, v0
	v_mov_b32_e32 v40, v0
	v_mov_b32_e32 v41, v0
	v_mov_b32_e32 v42, v0
	v_mov_b32_e32 v43, v0
	v_mov_b32_e32 v44, v0
	v_mov_b32_e32 v45, v0
	v_mov_b32_e32 v46, v0
	v_mov_b32_e32 v47, v0
	v_mov_b32_e32 v56, v0
	v_mov_b32_e32 v57, v0
	v_mov_b32_e32 v58, v0
	v_mov_b32_e32 v59, v0
	v_mov_b32_e32 v60, v0
	v_mov_b32_e32 v61, v0
	v_mov_b32_e32 v62, v0
	v_mov_b32_e32 v63, v0
	v_mov_b32_e32 v64, v0
	v_mov_b32_e32 v65, v0
	v_mov_b32_e32 v66, v0
	v_mov_b32_e32 v67, v0
	v_mov_b32_e32 v68, v0
	v_mov_b32_e32 v69, v0
	v_mov_b32_e32 v70, v0
	v_mov_b32_e32 v71, v0
	v_mov_b32_e32 v80, v0
	v_mov_b32_e32 v81, v0
	v_mov_b32_e32 v82, v0
	v_mov_b32_e32 v83, v0
	v_mov_b32_e32 v84, v0
	v_mov_b32_e32 v85, v0
	v_mov_b32_e32 v86, v0
	v_mov_b32_e32 v87, v0
	v_mov_b32_e32 v96, v0
	v_mov_b32_e32 v97, v0
	v_mov_b32_e32 v98, v0
	v_mov_b32_e32 v99, v0
	v_mov_b32_e32 v100, v0
	v_mov_b32_e32 v101, v0
	v_mov_b32_e32 v102, v0
	v_mov_b32_e32 v103, v0
	v_mov_b32_e32 v112, v0
	v_mov_b32_e32 v113, v0
	v_mov_b32_e32 v114, v0
	v_mov_b32_e32 v115, v0
	v_mov_b32_e32 v116, v0
	v_mov_b32_e32 v117, v0
	v_mov_b32_e32 v118, v0
	v_mov_b32_e32 v119, v0
	v_mov_b32_e32 v72, v0
	v_mov_b32_e32 v73, v0
	v_mov_b32_e32 v74, v0
	v_mov_b32_e32 v75, v0
	v_mov_b32_e32 v76, v0
	v_mov_b32_e32 v77, v0
	v_mov_b32_e32 v78, v0
	v_mov_b32_e32 v79, v0
	v_mov_b32_e32 v88, v0
	v_mov_b32_e32 v89, v0
	v_mov_b32_e32 v90, v0
	v_mov_b32_e32 v91, v0
	v_mov_b32_e32 v92, v0
	v_mov_b32_e32 v93, v0
	v_mov_b32_e32 v94, v0
	v_mov_b32_e32 v95, v0
	v_mov_b32_e32 v104, v0
	v_mov_b32_e32 v105, v0
	v_mov_b32_e32 v106, v0
	v_mov_b32_e32 v107, v0
	v_mov_b32_e32 v108, v0
	v_mov_b32_e32 v109, v0
	v_mov_b32_e32 v110, v0
	v_mov_b32_e32 v111, v0
	v_mov_b32_e32 v120, v0
	v_mov_b32_e32 v121, v0
	v_mov_b32_e32 v122, v0
	v_mov_b32_e32 v123, v0
	v_mov_b32_e32 v124, v0
	v_mov_b32_e32 v125, v0
	v_mov_b32_e32 v126, v0
	v_mov_b32_e32 v127, v0
	s_branch .LBB0_1332

.LBB0_1435:
	ds_read_b128 v[128:131], v180
	ds_read_b128 v[132:135], v180 offset:1024
	ds_read_b128 v[136:139], v180 offset:2048
	ds_read_b128 v[140:143], v180 offset:3072
	ds_read_b128 v[144:147], v181
	ds_read_b128 v[148:151], v181 offset:1024
	ds_read_b128 v[170:173], v181 offset:2048
	ds_read_b128 v[174:177], v181 offset:3072
	s_add_u32 s26, s24, 0xfffc0080
	s_addc_u32 s27, s25, -1
	s_cmp_eq_u32 s35, 12
	s_cselect_b32 s29, s1, s27
	s_cselect_b32 s28, s19, s26
	s_cselect_b32 s27, s17, s34
	s_cselect_b32 s26, s30, s31
	v_lshl_add_u64 v[184:185], s[24:25], 0, v[162:163]
	s_add_i32 m0, s40, 0xc000
	s_nop 0
	global_load_lds_dwordx4 v[184:185], off
	v_lshl_add_u64 v[184:185], s[24:25], 0, v[164:165]
	s_add_i32 m0, s40, 0xe000
	s_nop 0
	global_load_lds_dwordx4 v[184:185], off
	ds_read_b128 v[184:187], v182
	ds_read_b128 v[188:191], v182 offset:1024
	ds_read_b128 v[192:195], v182 offset:2048
	ds_read_b128 v[196:199], v182 offset:3072
	ds_read_b128 v[200:203], v182 offset:4096
	ds_read_b128 v[204:207], v182 offset:5120
	ds_read_b128 v[208:211], v182 offset:6144
	ds_read_b128 v[212:215], v182 offset:7168
	s_setprio 0
	s_waitcnt vmcnt(8)
	s_waitcnt lgkmcnt(0)
	s_barrier
	s_waitcnt lgkmcnt(0)
	v_mfma_f32_16x16x32_bf16 v[124:127], v[128:131], v[184:187], v[124:127]
	v_mfma_f32_16x16x32_bf16 v[124:127], v[132:135], v[188:191], v[124:127]
	v_mfma_f32_16x16x32_bf16 v[120:123], v[140:143], v[188:191], v[120:123]
	v_mfma_f32_16x16x32_bf16 v[120:123], v[136:139], v[184:187], v[120:123]
	v_mfma_f32_16x16x32_bf16 v[116:119], v[144:147], v[184:187], v[116:119]
	v_mfma_f32_16x16x32_bf16 v[116:119], v[148:151], v[188:191], v[116:119]
	v_mfma_f32_16x16x32_bf16 v[112:115], v[174:177], v[188:191], v[112:115]
	v_mfma_f32_16x16x32_bf16 v[112:115], v[170:173], v[184:187], v[112:115]
	v_mfma_f32_16x16x32_bf16 v[96:99], v[170:173], v[192:195], v[96:99]
	v_mfma_f32_16x16x32_bf16 v[96:99], v[174:177], v[196:199], v[96:99]
	v_mfma_f32_16x16x32_bf16 v[100:103], v[148:151], v[196:199], v[100:103]
	v_mfma_f32_16x16x32_bf16 v[100:103], v[144:147], v[192:195], v[100:103]
	v_mfma_f32_16x16x32_bf16 v[104:107], v[136:139], v[192:195], v[104:107]
	v_mfma_f32_16x16x32_bf16 v[104:107], v[140:143], v[196:199], v[104:107]
	v_mfma_f32_16x16x32_bf16 v[108:111], v[132:135], v[196:199], v[108:111]
	v_mfma_f32_16x16x32_bf16 v[108:111], v[128:131], v[192:195], v[108:111]
	v_mfma_f32_16x16x32_bf16 v[92:95], v[128:131], v[200:203], v[92:95]
	v_mfma_f32_16x16x32_bf16 v[92:95], v[132:135], v[204:207], v[92:95]
	v_mfma_f32_16x16x32_bf16 v[88:91], v[140:143], v[204:207], v[88:91]
	v_mfma_f32_16x16x32_bf16 v[88:91], v[136:139], v[200:203], v[88:91]
	v_mfma_f32_16x16x32_bf16 v[84:87], v[144:147], v[200:203], v[84:87]
	v_mfma_f32_16x16x32_bf16 v[84:87], v[148:151], v[204:207], v[84:87]
	v_mfma_f32_16x16x32_bf16 v[80:83], v[174:177], v[204:207], v[80:83]
	v_mfma_f32_16x16x32_bf16 v[80:83], v[170:173], v[200:203], v[80:83]
	v_mfma_f32_16x16x32_bf16 v[64:67], v[170:173], v[208:211], v[64:67]
	v_mfma_f32_16x16x32_bf16 v[64:67], v[174:177], v[212:215], v[64:67]
	v_mfma_f32_16x16x32_bf16 v[68:71], v[148:151], v[212:215], v[68:71]
	v_mfma_f32_16x16x32_bf16 v[68:71], v[144:147], v[208:211], v[68:71]
	v_mfma_f32_16x16x32_bf16 v[72:75], v[136:139], v[208:211], v[72:75]
	v_mfma_f32_16x16x32_bf16 v[72:75], v[140:143], v[212:215], v[72:75]
	v_mfma_f32_16x16x32_bf16 v[76:79], v[132:135], v[212:215], v[76:79]
	v_mfma_f32_16x16x32_bf16 v[76:79], v[128:131], v[208:211], v[76:79]
	s_barrier
	s_setprio 1
	s_add_i32 s54, s50, s39
	v_lshl_add_u64 v[216:217], s[26:27], 0, v[154:155]
	s_mov_b32 m0, s54
	v_lshl_add_u64 v[218:219], s[26:27], 0, v[158:159]
	global_load_lds_dwordx4 v[216:217], off
	s_add_i32 m0, s54, 0x2000
	s_add_u32 s54, s26, 0x100000
	s_addc_u32 s55, s27, 0
	s_add_i32 s56, s51, s39
	global_load_lds_dwordx4 v[218:219], off
	v_lshl_add_u64 v[184:185], s[54:55], 0, v[154:155]
	s_mov_b32 m0, s56
	v_lshl_add_u64 v[220:221], s[28:29], 0, v[152:153]
	global_load_lds_dwordx4 v[184:185], off
	v_lshl_add_u64 v[184:185], s[54:55], 0, v[158:159]
	s_add_i32 m0, s56, 0x2000
	v_lshl_add_u64 v[222:223], s[28:29], 0, v[156:157]
	global_load_lds_dwordx4 v[184:185], off
	s_mov_b32 m0, s40
	s_nop 0
	global_load_lds_dwordx4 v[220:221], off
	s_mov_b32 m0, s41
	s_nop 0
	global_load_lds_dwordx4 v[222:223], off
	ds_read_b128 v[184:187], v182 offset:16384
	ds_read_b128 v[188:191], v182 offset:17408
	ds_read_b128 v[192:195], v182 offset:18432
	ds_read_b128 v[196:199], v182 offset:19456
	ds_read_b128 v[200:203], v182 offset:20480
	ds_read_b128 v[204:207], v182 offset:21504
	ds_read_b128 v[208:211], v182 offset:22528
	ds_read_b128 v[212:215], v182 offset:23552
	s_setprio 0
	s_waitcnt vmcnt(8)
	s_waitcnt lgkmcnt(0)
	s_barrier
	s_waitcnt lgkmcnt(0)
	v_mfma_f32_16x16x32_bf16 v[60:63], v[128:131], v[184:187], v[60:63]
	v_mfma_f32_16x16x32_bf16 v[60:63], v[132:135], v[188:191], v[60:63]
	v_mfma_f32_16x16x32_bf16 v[56:59], v[140:143], v[188:191], v[56:59]
	v_mfma_f32_16x16x32_bf16 v[56:59], v[136:139], v[184:187], v[56:59]
	v_mfma_f32_16x16x32_bf16 v[52:55], v[144:147], v[184:187], v[52:55]
	v_mfma_f32_16x16x32_bf16 v[52:55], v[148:151], v[188:191], v[52:55]
	v_mfma_f32_16x16x32_bf16 v[48:51], v[174:177], v[188:191], v[48:51]
	v_mfma_f32_16x16x32_bf16 v[48:51], v[170:173], v[184:187], v[48:51]
	v_mfma_f32_16x16x32_bf16 v[32:35], v[170:173], v[192:195], v[32:35]
	v_mfma_f32_16x16x32_bf16 v[32:35], v[174:177], v[196:199], v[32:35]
	v_mfma_f32_16x16x32_bf16 v[36:39], v[148:151], v[196:199], v[36:39]
	v_mfma_f32_16x16x32_bf16 v[36:39], v[144:147], v[192:195], v[36:39]
	v_mfma_f32_16x16x32_bf16 v[40:43], v[136:139], v[192:195], v[40:43]
	v_mfma_f32_16x16x32_bf16 v[40:43], v[140:143], v[196:199], v[40:43]
	v_mfma_f32_16x16x32_bf16 v[44:47], v[132:135], v[196:199], v[44:47]
	v_mfma_f32_16x16x32_bf16 v[44:47], v[128:131], v[192:195], v[44:47]
	v_mfma_f32_16x16x32_bf16 v[28:31], v[128:131], v[200:203], v[28:31]
	v_mfma_f32_16x16x32_bf16 v[28:31], v[132:135], v[204:207], v[28:31]
	v_mfma_f32_16x16x32_bf16 v[24:27], v[140:143], v[204:207], v[24:27]
	v_mfma_f32_16x16x32_bf16 v[24:27], v[136:139], v[200:203], v[24:27]
	v_mfma_f32_16x16x32_bf16 v[20:23], v[144:147], v[200:203], v[20:23]
	v_mfma_f32_16x16x32_bf16 v[20:23], v[148:151], v[204:207], v[20:23]
	v_mfma_f32_16x16x32_bf16 v[16:19], v[174:177], v[204:207], v[16:19]
	v_mfma_f32_16x16x32_bf16 v[16:19], v[170:173], v[200:203], v[16:19]
	v_mfma_f32_16x16x32_bf16 v[0:3], v[170:173], v[208:211], v[0:3]
	v_mfma_f32_16x16x32_bf16 v[0:3], v[174:177], v[212:215], v[0:3]
	v_mfma_f32_16x16x32_bf16 v[4:7], v[148:151], v[212:215], v[4:7]
	v_mfma_f32_16x16x32_bf16 v[4:7], v[144:147], v[208:211], v[4:7]
	v_mfma_f32_16x16x32_bf16 v[8:11], v[136:139], v[208:211], v[8:11]
	v_mfma_f32_16x16x32_bf16 v[8:11], v[140:143], v[212:215], v[8:11]
	v_mfma_f32_16x16x32_bf16 v[12:15], v[132:135], v[212:215], v[12:15]
	v_mfma_f32_16x16x32_bf16 v[12:15], v[128:131], v[208:211], v[12:15]
	s_barrier
	s_setprio 1
	s_add_i32 s54, 0, 0x18000
	s_add_i32 s55, 0, 0x1c000
	v_add_u32_e32 v140, s54, v178
	v_add_u32_e32 v174, s55, v178
	ds_read_b128 v[128:131], v140
	ds_read_b128 v[132:135], v140 offset:1024
	ds_read_b128 v[136:139], v140 offset:2048
	ds_read_b128 v[140:143], v140 offset:3072
	ds_read_b128 v[144:147], v174
	ds_read_b128 v[148:151], v174 offset:1024
	ds_read_b128 v[170:173], v174 offset:2048
	ds_read_b128 v[174:177], v174 offset:3072
	s_add_u32 s28, s28, 0x40000
	s_addc_u32 s29, s29, 0
	s_mov_b32 m0, s42
	v_lshl_add_u64 v[184:185], s[28:29], 0, v[152:153]
	global_load_lds_dwordx4 v[184:185], off
	v_lshl_add_u64 v[184:185], s[28:29], 0, v[156:157]
	s_mov_b32 m0, s43
	s_nop 0
	global_load_lds_dwordx4 v[184:185], off
	ds_read_b128 v[184:187], v182 offset:32768
	ds_read_b128 v[188:191], v182 offset:33792
	ds_read_b128 v[192:195], v182 offset:34816
	ds_read_b128 v[196:199], v182 offset:35840
	ds_read_b128 v[200:203], v182 offset:36864
	ds_read_b128 v[204:207], v182 offset:37888
	ds_read_b128 v[208:211], v182 offset:38912
	ds_read_b128 v[212:215], v182 offset:39936
	s_setprio 0
	s_waitcnt vmcnt(8)
	s_waitcnt lgkmcnt(0)
	s_barrier
	s_waitcnt lgkmcnt(0)
	v_mfma_f32_16x16x32_bf16 v[124:127], v[128:131], v[184:187], v[124:127]
	v_mfma_f32_16x16x32_bf16 v[124:127], v[132:135], v[188:191], v[124:127]
	v_mfma_f32_16x16x32_bf16 v[120:123], v[140:143], v[188:191], v[120:123]
	v_mfma_f32_16x16x32_bf16 v[120:123], v[136:139], v[184:187], v[120:123]
	v_mfma_f32_16x16x32_bf16 v[116:119], v[144:147], v[184:187], v[116:119]
	v_mfma_f32_16x16x32_bf16 v[116:119], v[148:151], v[188:191], v[116:119]
	v_mfma_f32_16x16x32_bf16 v[112:115], v[174:177], v[188:191], v[112:115]
	v_mfma_f32_16x16x32_bf16 v[112:115], v[170:173], v[184:187], v[112:115]
	v_mfma_f32_16x16x32_bf16 v[96:99], v[170:173], v[192:195], v[96:99]
	v_mfma_f32_16x16x32_bf16 v[96:99], v[174:177], v[196:199], v[96:99]
	v_mfma_f32_16x16x32_bf16 v[100:103], v[148:151], v[196:199], v[100:103]
	v_mfma_f32_16x16x32_bf16 v[100:103], v[144:147], v[192:195], v[100:103]
	v_mfma_f32_16x16x32_bf16 v[104:107], v[136:139], v[192:195], v[104:107]
	v_mfma_f32_16x16x32_bf16 v[104:107], v[140:143], v[196:199], v[104:107]
	v_mfma_f32_16x16x32_bf16 v[108:111], v[132:135], v[196:199], v[108:111]
	v_mfma_f32_16x16x32_bf16 v[108:111], v[128:131], v[192:195], v[108:111]
	v_mfma_f32_16x16x32_bf16 v[92:95], v[128:131], v[200:203], v[92:95]
	v_mfma_f32_16x16x32_bf16 v[92:95], v[132:135], v[204:207], v[92:95]
	v_mfma_f32_16x16x32_bf16 v[88:91], v[140:143], v[204:207], v[88:91]
	v_mfma_f32_16x16x32_bf16 v[88:91], v[136:139], v[200:203], v[88:91]
	v_mfma_f32_16x16x32_bf16 v[84:87], v[144:147], v[200:203], v[84:87]
	v_mfma_f32_16x16x32_bf16 v[84:87], v[148:151], v[204:207], v[84:87]
	v_mfma_f32_16x16x32_bf16 v[80:83], v[174:177], v[204:207], v[80:83]
	v_mfma_f32_16x16x32_bf16 v[80:83], v[170:173], v[200:203], v[80:83]
	v_mfma_f32_16x16x32_bf16 v[64:67], v[170:173], v[208:211], v[64:67]
	v_mfma_f32_16x16x32_bf16 v[64:67], v[174:177], v[212:215], v[64:67]
	v_mfma_f32_16x16x32_bf16 v[68:71], v[148:151], v[212:215], v[68:71]
	v_mfma_f32_16x16x32_bf16 v[68:71], v[144:147], v[208:211], v[68:71]
	v_mfma_f32_16x16x32_bf16 v[72:75], v[136:139], v[208:211], v[72:75]
	v_mfma_f32_16x16x32_bf16 v[72:75], v[140:143], v[212:215], v[72:75]
	v_mfma_f32_16x16x32_bf16 v[76:79], v[132:135], v[212:215], v[76:79]
	v_mfma_f32_16x16x32_bf16 v[76:79], v[128:131], v[208:211], v[76:79]
	s_barrier
	s_setprio 1
	s_add_i32 s28, s54, s39
	v_lshl_add_u64 v[184:185], v[216:217], 0, s[14:15]
	s_mov_b32 m0, s28
	s_nop 0
	global_load_lds_dwordx4 v[184:185], off
	s_add_i32 m0, s28, 0x2000
	s_add_u32 s26, s26, 0x100080
	v_lshl_add_u64 v[184:185], v[218:219], 0, s[14:15]
	s_addc_u32 s27, s27, 0
	s_add_i32 s28, s55, s39
	global_load_lds_dwordx4 v[184:185], off
	v_lshl_add_u64 v[184:185], s[26:27], 0, v[154:155]
	s_mov_b32 m0, s28
	s_nop 0
	global_load_lds_dwordx4 v[184:185], off
	v_lshl_add_u64 v[184:185], s[26:27], 0, v[158:159]
	s_add_i32 m0, s28, 0x2000
	s_nop 0
	global_load_lds_dwordx4 v[184:185], off
	v_lshl_add_u64 v[184:185], v[220:221], 0, s[14:15]
	s_mov_b32 m0, s45
	s_nop 0
	global_load_lds_dwordx4 v[184:185], off
	v_lshl_add_u64 v[184:185], v[222:223], 0, s[14:15]
	s_mov_b32 m0, s46
	s_nop 0
	global_load_lds_dwordx4 v[184:185], off
	ds_read_b128 v[184:187], v182 offset:49152
	ds_read_b128 v[188:191], v182 offset:50176
	ds_read_b128 v[192:195], v182 offset:51200
	ds_read_b128 v[196:199], v182 offset:52224
	ds_read_b128 v[200:203], v182 offset:53248
	ds_read_b128 v[204:207], v182 offset:54272
	ds_read_b128 v[208:211], v182 offset:55296
	ds_read_b128 v[212:215], v182 offset:56320
	s_setprio 0
	s_waitcnt vmcnt(8)
	s_waitcnt lgkmcnt(0)
	s_barrier
	s_waitcnt lgkmcnt(0)
	v_mfma_f32_16x16x32_bf16 v[60:63], v[128:131], v[184:187], v[60:63]
	v_mfma_f32_16x16x32_bf16 v[60:63], v[132:135], v[188:191], v[60:63]
	v_mfma_f32_16x16x32_bf16 v[56:59], v[140:143], v[188:191], v[56:59]
	v_mfma_f32_16x16x32_bf16 v[56:59], v[136:139], v[184:187], v[56:59]
	v_mfma_f32_16x16x32_bf16 v[52:55], v[144:147], v[184:187], v[52:55]
	v_mfma_f32_16x16x32_bf16 v[52:55], v[148:151], v[188:191], v[52:55]
	v_mfma_f32_16x16x32_bf16 v[48:51], v[174:177], v[188:191], v[48:51]
	v_mfma_f32_16x16x32_bf16 v[48:51], v[170:173], v[184:187], v[48:51]
	v_mfma_f32_16x16x32_bf16 v[32:35], v[170:173], v[192:195], v[32:35]
	v_mfma_f32_16x16x32_bf16 v[32:35], v[174:177], v[196:199], v[32:35]
	v_mfma_f32_16x16x32_bf16 v[36:39], v[148:151], v[196:199], v[36:39]
	v_mfma_f32_16x16x32_bf16 v[36:39], v[144:147], v[192:195], v[36:39]
	v_mfma_f32_16x16x32_bf16 v[40:43], v[136:139], v[192:195], v[40:43]
	v_mfma_f32_16x16x32_bf16 v[40:43], v[140:143], v[196:199], v[40:43]
	v_mfma_f32_16x16x32_bf16 v[44:47], v[132:135], v[196:199], v[44:47]
	v_mfma_f32_16x16x32_bf16 v[44:47], v[128:131], v[192:195], v[44:47]
	v_mfma_f32_16x16x32_bf16 v[28:31], v[128:131], v[200:203], v[28:31]
	v_mfma_f32_16x16x32_bf16 v[28:31], v[132:135], v[204:207], v[28:31]
	v_mfma_f32_16x16x32_bf16 v[24:27], v[140:143], v[204:207], v[24:27]
	v_mfma_f32_16x16x32_bf16 v[24:27], v[136:139], v[200:203], v[24:27]
	v_mfma_f32_16x16x32_bf16 v[20:23], v[144:147], v[200:203], v[20:23]
	v_mfma_f32_16x16x32_bf16 v[20:23], v[148:151], v[204:207], v[20:23]
	v_mfma_f32_16x16x32_bf16 v[16:19], v[174:177], v[204:207], v[16:19]
	v_mfma_f32_16x16x32_bf16 v[16:19], v[170:173], v[200:203], v[16:19]
	v_mfma_f32_16x16x32_bf16 v[0:3], v[170:173], v[208:211], v[0:3]
	v_mfma_f32_16x16x32_bf16 v[0:3], v[174:177], v[212:215], v[0:3]
	v_mfma_f32_16x16x32_bf16 v[4:7], v[148:151], v[212:215], v[4:7]
	v_mfma_f32_16x16x32_bf16 v[4:7], v[144:147], v[208:211], v[4:7]
	v_mfma_f32_16x16x32_bf16 v[8:11], v[136:139], v[208:211], v[8:11]
	v_mfma_f32_16x16x32_bf16 v[8:11], v[140:143], v[212:215], v[8:11]
	v_mfma_f32_16x16x32_bf16 v[12:15], v[132:135], v[212:215], v[12:15]
	v_mfma_f32_16x16x32_bf16 v[12:15], v[128:131], v[208:211], v[12:15]
	s_barrier
	s_setprio 1
	s_add_i32 s35, s35, 2
	s_add_u32 s24, s24, 0x100
	s_addc_u32 s25, s25, 0
	s_add_u32 s31, s31, 0x100
	s_addc_u32 s34, s34, 0
	s_cmp_gt_u32 s35, 13
	s_cbranch_scc0 .LBB0_1435
	s_setprio 0
	s_and_b64 vcc, exec, s[8:9]
	s_cbranch_vccz .LBB0_1438
	s_barrier

.LBB0_1543:
	ds_read_b128 v[128:131], v167
	ds_read_b128 v[154:157], v167 offset:1024
	ds_read_b128 v[172:175], v167 offset:2048
	ds_read_b128 v[176:179], v167 offset:3072
	ds_read_b128 v[180:183], v168
	ds_read_b128 v[184:187], v168 offset:1024
	ds_read_b128 v[188:191], v168 offset:2048
	ds_read_b128 v[192:195], v168 offset:3072
	s_add_u32 s22, s20, 0x1000
	s_addc_u32 s23, s21, 0
	s_cmp_eq_u32 s54, 60
	s_cselect_b32 s27, s13, s23
	s_cselect_b32 s26, s50, s22
	s_cselect_b32 s25, s11, s53
	s_cselect_b32 s24, s51, s52
	v_lshl_add_u64 v[160:161], s[20:21], 0, v[144:145]
	s_add_i32 m0, s19, 0xc000
	s_nop 0
	global_load_lds_dwordx4 v[160:161], off
	v_lshl_add_u64 v[160:161], s[20:21], 0, v[146:147]
	s_add_i32 m0, s19, 0xe000
	s_nop 0
	global_load_lds_dwordx4 v[160:161], off
	ds_read_b128 v[196:199], v169
	ds_read_b128 v[200:203], v169 offset:1024
	ds_read_b128 v[204:207], v169 offset:2048
	ds_read_b128 v[208:211], v169 offset:3072
	ds_read_b128 v[212:215], v169 offset:4096
	ds_read_b128 v[216:219], v169 offset:5120
	ds_read_b128 v[220:223], v169 offset:6144
	ds_read_b128 v[224:227], v169 offset:7168
	s_setprio 0
	s_waitcnt vmcnt(8)
	s_waitcnt lgkmcnt(0)
	s_barrier
	s_waitcnt lgkmcnt(0)
	v_mfma_f32_16x16x32_bf16 v[124:127], v[128:131], v[196:199], v[124:127]
	v_mfma_f32_16x16x32_bf16 v[124:127], v[154:157], v[200:203], v[124:127]
	v_mfma_f32_16x16x32_bf16 v[120:123], v[176:179], v[200:203], v[120:123]
	v_mfma_f32_16x16x32_bf16 v[120:123], v[172:175], v[196:199], v[120:123]
	v_mfma_f32_16x16x32_bf16 v[116:119], v[180:183], v[196:199], v[116:119]
	v_mfma_f32_16x16x32_bf16 v[116:119], v[184:187], v[200:203], v[116:119]
	v_mfma_f32_16x16x32_bf16 v[112:115], v[192:195], v[200:203], v[112:115]
	v_mfma_f32_16x16x32_bf16 v[112:115], v[188:191], v[196:199], v[112:115]
	v_mfma_f32_16x16x32_bf16 v[96:99], v[188:191], v[204:207], v[96:99]
	v_mfma_f32_16x16x32_bf16 v[96:99], v[192:195], v[208:211], v[96:99]
	v_mfma_f32_16x16x32_bf16 v[100:103], v[184:187], v[208:211], v[100:103]
	v_mfma_f32_16x16x32_bf16 v[100:103], v[180:183], v[204:207], v[100:103]
	v_mfma_f32_16x16x32_bf16 v[104:107], v[172:175], v[204:207], v[104:107]
	v_mfma_f32_16x16x32_bf16 v[104:107], v[176:179], v[208:211], v[104:107]
	v_mfma_f32_16x16x32_bf16 v[108:111], v[154:157], v[208:211], v[108:111]
	v_mfma_f32_16x16x32_bf16 v[108:111], v[128:131], v[204:207], v[108:111]
	v_mfma_f32_16x16x32_bf16 v[92:95], v[128:131], v[212:215], v[92:95]
	v_mfma_f32_16x16x32_bf16 v[92:95], v[154:157], v[216:219], v[92:95]
	v_mfma_f32_16x16x32_bf16 v[88:91], v[176:179], v[216:219], v[88:91]
	v_mfma_f32_16x16x32_bf16 v[88:91], v[172:175], v[212:215], v[88:91]
	v_mfma_f32_16x16x32_bf16 v[84:87], v[180:183], v[212:215], v[84:87]
	v_mfma_f32_16x16x32_bf16 v[84:87], v[184:187], v[216:219], v[84:87]
	v_mfma_f32_16x16x32_bf16 v[80:83], v[192:195], v[216:219], v[80:83]
	v_mfma_f32_16x16x32_bf16 v[80:83], v[188:191], v[212:215], v[80:83]
	v_mfma_f32_16x16x32_bf16 v[64:67], v[188:191], v[220:223], v[64:67]
	v_mfma_f32_16x16x32_bf16 v[64:67], v[192:195], v[224:227], v[64:67]
	v_mfma_f32_16x16x32_bf16 v[68:71], v[184:187], v[224:227], v[68:71]
	v_mfma_f32_16x16x32_bf16 v[68:71], v[180:183], v[220:223], v[68:71]
	v_mfma_f32_16x16x32_bf16 v[72:75], v[172:175], v[220:223], v[72:75]
	v_mfma_f32_16x16x32_bf16 v[72:75], v[176:179], v[224:227], v[72:75]
	v_mfma_f32_16x16x32_bf16 v[76:79], v[154:157], v[224:227], v[76:79]
	v_mfma_f32_16x16x32_bf16 v[76:79], v[128:131], v[220:223], v[76:79]
	s_barrier
	s_setprio 1
	s_add_i32 s20, s45, s30
	v_lshl_add_u64 v[160:161], s[24:25], 0, v[134:135]
	s_mov_b32 m0, s20
	v_lshl_add_u64 v[164:165], s[24:25], 0, v[138:139]
	global_load_lds_dwordx4 v[160:161], off
	s_add_i32 m0, s20, 0x2000
	s_add_u32 s20, s24, 0x100000
	s_addc_u32 s21, s25, 0
	s_add_i32 s55, s46, s30
	global_load_lds_dwordx4 v[164:165], off
	v_lshl_add_u64 v[196:197], s[20:21], 0, v[134:135]
	s_mov_b32 m0, s55
	v_lshl_add_u64 v[228:229], s[26:27], 0, v[132:133]
	global_load_lds_dwordx4 v[196:197], off
	v_lshl_add_u64 v[196:197], s[20:21], 0, v[138:139]
	s_add_i32 m0, s55, 0x2000
	v_lshl_add_u64 v[230:231], s[26:27], 0, v[136:137]
	global_load_lds_dwordx4 v[196:197], off
	s_mov_b32 m0, s19
	s_nop 0
	global_load_lds_dwordx4 v[228:229], off
	s_mov_b32 m0, s36
	s_nop 0
	global_load_lds_dwordx4 v[230:231], off
	ds_read_b128 v[196:199], v169 offset:16384
	ds_read_b128 v[200:203], v169 offset:17408
	ds_read_b128 v[204:207], v169 offset:18432
	ds_read_b128 v[208:211], v169 offset:19456
	ds_read_b128 v[212:215], v169 offset:20480
	ds_read_b128 v[216:219], v169 offset:21504
	ds_read_b128 v[220:223], v169 offset:22528
	ds_read_b128 v[224:227], v169 offset:23552
	s_setprio 0
	s_waitcnt vmcnt(8)
	s_waitcnt lgkmcnt(0)
	s_barrier
	s_waitcnt lgkmcnt(0)
	v_mfma_f32_16x16x32_bf16 v[60:63], v[128:131], v[196:199], v[60:63]
	v_mfma_f32_16x16x32_bf16 v[60:63], v[154:157], v[200:203], v[60:63]
	v_mfma_f32_16x16x32_bf16 v[56:59], v[176:179], v[200:203], v[56:59]
	v_mfma_f32_16x16x32_bf16 v[56:59], v[172:175], v[196:199], v[56:59]
	v_mfma_f32_16x16x32_bf16 v[52:55], v[180:183], v[196:199], v[52:55]
	v_mfma_f32_16x16x32_bf16 v[52:55], v[184:187], v[200:203], v[52:55]
	v_mfma_f32_16x16x32_bf16 v[48:51], v[192:195], v[200:203], v[48:51]
	v_mfma_f32_16x16x32_bf16 v[48:51], v[188:191], v[196:199], v[48:51]
	v_mfma_f32_16x16x32_bf16 v[32:35], v[188:191], v[204:207], v[32:35]
	v_mfma_f32_16x16x32_bf16 v[32:35], v[192:195], v[208:211], v[32:35]
	v_mfma_f32_16x16x32_bf16 v[36:39], v[184:187], v[208:211], v[36:39]
	v_mfma_f32_16x16x32_bf16 v[36:39], v[180:183], v[204:207], v[36:39]
	v_mfma_f32_16x16x32_bf16 v[40:43], v[172:175], v[204:207], v[40:43]
	v_mfma_f32_16x16x32_bf16 v[40:43], v[176:179], v[208:211], v[40:43]
	v_mfma_f32_16x16x32_bf16 v[44:47], v[154:157], v[208:211], v[44:47]
	v_mfma_f32_16x16x32_bf16 v[44:47], v[128:131], v[204:207], v[44:47]
	v_mfma_f32_16x16x32_bf16 v[28:31], v[128:131], v[212:215], v[28:31]
	v_mfma_f32_16x16x32_bf16 v[28:31], v[154:157], v[216:219], v[28:31]
	v_mfma_f32_16x16x32_bf16 v[24:27], v[176:179], v[216:219], v[24:27]
	v_mfma_f32_16x16x32_bf16 v[24:27], v[172:175], v[212:215], v[24:27]
	v_mfma_f32_16x16x32_bf16 v[20:23], v[180:183], v[212:215], v[20:23]
	v_mfma_f32_16x16x32_bf16 v[20:23], v[184:187], v[216:219], v[20:23]
	v_mfma_f32_16x16x32_bf16 v[16:19], v[192:195], v[216:219], v[16:19]
	v_mfma_f32_16x16x32_bf16 v[16:19], v[188:191], v[212:215], v[16:19]
	v_mfma_f32_16x16x32_bf16 v[0:3], v[188:191], v[220:223], v[0:3]
	v_mfma_f32_16x16x32_bf16 v[0:3], v[192:195], v[224:227], v[0:3]
	v_mfma_f32_16x16x32_bf16 v[4:7], v[184:187], v[224:227], v[4:7]
	v_mfma_f32_16x16x32_bf16 v[4:7], v[180:183], v[220:223], v[4:7]
	v_mfma_f32_16x16x32_bf16 v[8:11], v[172:175], v[220:223], v[8:11]
	v_mfma_f32_16x16x32_bf16 v[8:11], v[176:179], v[224:227], v[8:11]
	v_mfma_f32_16x16x32_bf16 v[12:15], v[154:157], v[224:227], v[12:15]
	v_mfma_f32_16x16x32_bf16 v[12:15], v[128:131], v[220:223], v[12:15]
	s_barrier
	s_setprio 1
	s_add_i32 s55, 0, 0x18000
	v_add_u32_e32 v153, s55, v159
	s_add_i32 s56, 0, 0x1c000
	ds_read_b128 v[128:131], v153
	ds_read_b128 v[154:157], v153 offset:1024
	ds_read_b128 v[172:175], v153 offset:2048
	ds_read_b128 v[176:179], v153 offset:3072
	v_add_u32_e32 v153, s56, v159
	ds_read_b128 v[180:183], v153
	ds_read_b128 v[184:187], v153 offset:1024
	ds_read_b128 v[188:191], v153 offset:2048
	ds_read_b128 v[192:195], v153 offset:3072
	s_add_u32 s20, s26, 0x100000
	s_addc_u32 s21, s27, 0
	s_mov_b32 m0, s37
	v_lshl_add_u64 v[196:197], s[20:21], 0, v[132:133]
	global_load_lds_dwordx4 v[196:197], off
	v_lshl_add_u64 v[196:197], s[20:21], 0, v[136:137]
	s_mov_b32 m0, s38
	s_nop 0
	global_load_lds_dwordx4 v[196:197], off
	ds_read_b128 v[196:199], v169 offset:32768
	ds_read_b128 v[200:203], v169 offset:33792
	ds_read_b128 v[204:207], v169 offset:34816
	ds_read_b128 v[208:211], v169 offset:35840
	ds_read_b128 v[212:215], v169 offset:36864
	ds_read_b128 v[216:219], v169 offset:37888
	ds_read_b128 v[220:223], v169 offset:38912
	ds_read_b128 v[224:227], v169 offset:39936
	s_setprio 0
	s_waitcnt vmcnt(8)
	s_waitcnt lgkmcnt(0)
	s_barrier
	s_waitcnt lgkmcnt(0)
	v_mfma_f32_16x16x32_bf16 v[124:127], v[128:131], v[196:199], v[124:127]
	v_mfma_f32_16x16x32_bf16 v[124:127], v[154:157], v[200:203], v[124:127]
	v_mfma_f32_16x16x32_bf16 v[120:123], v[176:179], v[200:203], v[120:123]
	v_mfma_f32_16x16x32_bf16 v[120:123], v[172:175], v[196:199], v[120:123]
	v_mfma_f32_16x16x32_bf16 v[116:119], v[180:183], v[196:199], v[116:119]
	v_mfma_f32_16x16x32_bf16 v[116:119], v[184:187], v[200:203], v[116:119]
	v_mfma_f32_16x16x32_bf16 v[112:115], v[192:195], v[200:203], v[112:115]
	v_mfma_f32_16x16x32_bf16 v[112:115], v[188:191], v[196:199], v[112:115]
	v_mfma_f32_16x16x32_bf16 v[96:99], v[188:191], v[204:207], v[96:99]
	v_mfma_f32_16x16x32_bf16 v[96:99], v[192:195], v[208:211], v[96:99]
	v_mfma_f32_16x16x32_bf16 v[100:103], v[184:187], v[208:211], v[100:103]
	v_mfma_f32_16x16x32_bf16 v[100:103], v[180:183], v[204:207], v[100:103]
	v_mfma_f32_16x16x32_bf16 v[104:107], v[172:175], v[204:207], v[104:107]
	v_mfma_f32_16x16x32_bf16 v[104:107], v[176:179], v[208:211], v[104:107]
	v_mfma_f32_16x16x32_bf16 v[108:111], v[154:157], v[208:211], v[108:111]
	v_mfma_f32_16x16x32_bf16 v[108:111], v[128:131], v[204:207], v[108:111]
	v_mfma_f32_16x16x32_bf16 v[92:95], v[128:131], v[212:215], v[92:95]
	v_mfma_f32_16x16x32_bf16 v[92:95], v[154:157], v[216:219], v[92:95]
	v_mfma_f32_16x16x32_bf16 v[88:91], v[176:179], v[216:219], v[88:91]
	v_mfma_f32_16x16x32_bf16 v[88:91], v[172:175], v[212:215], v[88:91]
	v_mfma_f32_16x16x32_bf16 v[84:87], v[180:183], v[212:215], v[84:87]
	v_mfma_f32_16x16x32_bf16 v[84:87], v[184:187], v[216:219], v[84:87]
	v_mfma_f32_16x16x32_bf16 v[80:83], v[192:195], v[216:219], v[80:83]
	v_mfma_f32_16x16x32_bf16 v[80:83], v[188:191], v[212:215], v[80:83]
	v_mfma_f32_16x16x32_bf16 v[64:67], v[188:191], v[220:223], v[64:67]
	v_mfma_f32_16x16x32_bf16 v[64:67], v[192:195], v[224:227], v[64:67]
	v_mfma_f32_16x16x32_bf16 v[68:71], v[184:187], v[224:227], v[68:71]
	v_mfma_f32_16x16x32_bf16 v[68:71], v[180:183], v[220:223], v[68:71]
	v_mfma_f32_16x16x32_bf16 v[72:75], v[172:175], v[220:223], v[72:75]
	v_mfma_f32_16x16x32_bf16 v[72:75], v[176:179], v[224:227], v[72:75]
	v_mfma_f32_16x16x32_bf16 v[76:79], v[154:157], v[224:227], v[76:79]
	v_mfma_f32_16x16x32_bf16 v[76:79], v[128:131], v[220:223], v[76:79]
	s_barrier
	s_setprio 1
	s_add_i32 s20, s55, s30
	v_lshl_add_u64 v[160:161], v[160:161], 0, s[8:9]
	s_mov_b32 m0, s20
	s_nop 0
	global_load_lds_dwordx4 v[160:161], off
	s_add_i32 m0, s20, 0x2000
	s_add_u32 s20, s24, 0x100800
	v_lshl_add_u64 v[160:161], v[164:165], 0, s[8:9]
	s_addc_u32 s21, s25, 0
	s_add_i32 s24, s56, s30
	global_load_lds_dwordx4 v[160:161], off
	v_lshl_add_u64 v[160:161], s[20:21], 0, v[134:135]
	s_mov_b32 m0, s24
	s_nop 0
	global_load_lds_dwordx4 v[160:161], off
	v_lshl_add_u64 v[160:161], s[20:21], 0, v[138:139]
	s_add_i32 m0, s24, 0x2000
	s_nop 0
	global_load_lds_dwordx4 v[160:161], off
	v_lshl_add_u64 v[160:161], v[228:229], 0, s[8:9]
	s_mov_b32 m0, s41
	s_nop 0
	global_load_lds_dwordx4 v[160:161], off
	v_lshl_add_u64 v[160:161], v[230:231], 0, s[8:9]
	s_mov_b32 m0, s42
	s_nop 0
	global_load_lds_dwordx4 v[160:161], off
	ds_read_b128 v[196:199], v169 offset:49152
	ds_read_b128 v[200:203], v169 offset:50176
	ds_read_b128 v[204:207], v169 offset:51200
	ds_read_b128 v[208:211], v169 offset:52224
	ds_read_b128 v[212:215], v169 offset:53248
	ds_read_b128 v[216:219], v169 offset:54272
	ds_read_b128 v[220:223], v169 offset:55296
	ds_read_b128 v[224:227], v169 offset:56320
	s_setprio 0
	s_waitcnt vmcnt(8)
	s_waitcnt lgkmcnt(0)
	s_barrier
	s_waitcnt lgkmcnt(0)
	v_mfma_f32_16x16x32_bf16 v[60:63], v[128:131], v[196:199], v[60:63]
	v_mfma_f32_16x16x32_bf16 v[60:63], v[154:157], v[200:203], v[60:63]
	v_mfma_f32_16x16x32_bf16 v[56:59], v[176:179], v[200:203], v[56:59]
	v_mfma_f32_16x16x32_bf16 v[56:59], v[172:175], v[196:199], v[56:59]
	v_mfma_f32_16x16x32_bf16 v[52:55], v[180:183], v[196:199], v[52:55]
	v_mfma_f32_16x16x32_bf16 v[52:55], v[184:187], v[200:203], v[52:55]
	v_mfma_f32_16x16x32_bf16 v[48:51], v[192:195], v[200:203], v[48:51]
	v_mfma_f32_16x16x32_bf16 v[48:51], v[188:191], v[196:199], v[48:51]
	v_mfma_f32_16x16x32_bf16 v[32:35], v[188:191], v[204:207], v[32:35]
	v_mfma_f32_16x16x32_bf16 v[32:35], v[192:195], v[208:211], v[32:35]
	v_mfma_f32_16x16x32_bf16 v[36:39], v[184:187], v[208:211], v[36:39]
	v_mfma_f32_16x16x32_bf16 v[36:39], v[180:183], v[204:207], v[36:39]
	v_mfma_f32_16x16x32_bf16 v[40:43], v[172:175], v[204:207], v[40:43]
	v_mfma_f32_16x16x32_bf16 v[40:43], v[176:179], v[208:211], v[40:43]
	v_mfma_f32_16x16x32_bf16 v[44:47], v[154:157], v[208:211], v[44:47]
	v_mfma_f32_16x16x32_bf16 v[44:47], v[128:131], v[204:207], v[44:47]
	v_mfma_f32_16x16x32_bf16 v[28:31], v[128:131], v[212:215], v[28:31]
	v_mfma_f32_16x16x32_bf16 v[28:31], v[154:157], v[216:219], v[28:31]
	v_mfma_f32_16x16x32_bf16 v[24:27], v[176:179], v[216:219], v[24:27]
	v_mfma_f32_16x16x32_bf16 v[24:27], v[172:175], v[212:215], v[24:27]
	v_mfma_f32_16x16x32_bf16 v[20:23], v[180:183], v[212:215], v[20:23]
	v_mfma_f32_16x16x32_bf16 v[20:23], v[184:187], v[216:219], v[20:23]
	v_mfma_f32_16x16x32_bf16 v[16:19], v[192:195], v[216:219], v[16:19]
	v_mfma_f32_16x16x32_bf16 v[16:19], v[188:191], v[212:215], v[16:19]
	v_mfma_f32_16x16x32_bf16 v[0:3], v[188:191], v[220:223], v[0:3]
	v_mfma_f32_16x16x32_bf16 v[0:3], v[192:195], v[224:227], v[0:3]
	v_mfma_f32_16x16x32_bf16 v[4:7], v[184:187], v[224:227], v[4:7]
	v_mfma_f32_16x16x32_bf16 v[4:7], v[180:183], v[220:223], v[4:7]
	v_mfma_f32_16x16x32_bf16 v[8:11], v[172:175], v[220:223], v[8:11]
	v_mfma_f32_16x16x32_bf16 v[8:11], v[176:179], v[224:227], v[8:11]
	v_mfma_f32_16x16x32_bf16 v[12:15], v[154:157], v[224:227], v[12:15]
	v_mfma_f32_16x16x32_bf16 v[12:15], v[128:131], v[220:223], v[12:15]
	s_barrier
	s_setprio 1
	s_add_i32 s54, s54, 2
	s_add_u32 s52, s52, 0x1000
	s_addc_u32 s53, s53, 0
	s_cmp_gt_u32 s54, 61
	s_mov_b64 s[20:21], s[22:23]
	s_cbranch_scc0 .LBB0_1543
	s_setprio 0
	s_and_b64 vcc, exec, s[4:5]
	s_cbranch_vccz .LBB0_1546
	s_barrier

.LBB0_1625:
	ds_read_b128 v[128:131], v177
	ds_read_b128 v[132:135], v177 offset:1024
	ds_read_b128 v[136:139], v177 offset:2048
	ds_read_b128 v[140:143], v177 offset:3072
	ds_read_b128 v[144:147], v178
	ds_read_b128 v[148:151], v178 offset:1024
	ds_read_b128 v[170:173], v178 offset:2048
	ds_read_b128 v[182:185], v178 offset:3072
	s_add_u32 s24, s22, 0xffc00800
	s_addc_u32 s25, s23, -1
	s_cmpk_eq_i32 s57, 0xfc
	s_cselect_b32 s27, s29, s25
	s_cselect_b32 s26, s53, s24
	s_cselect_b32 s25, s17, s56
	s_cselect_b32 s24, s54, s55
	v_lshl_add_u64 v[186:187], s[22:23], 0, v[162:163]
	s_add_i32 m0, s38, 0xc000
	s_nop 0
	global_load_lds_dwordx4 v[186:187], off
	v_lshl_add_u64 v[186:187], s[22:23], 0, v[164:165]
	s_add_i32 m0, s38, 0xe000
	s_nop 0
	global_load_lds_dwordx4 v[186:187], off
	ds_read_b128 v[186:189], v179
	ds_read_b128 v[190:193], v179 offset:1024
	ds_read_b128 v[194:197], v179 offset:2048
	ds_read_b128 v[198:201], v179 offset:3072
	ds_read_b128 v[202:205], v179 offset:4096
	ds_read_b128 v[206:209], v179 offset:5120
	ds_read_b128 v[210:213], v179 offset:6144
	ds_read_b128 v[214:217], v179 offset:7168
	s_setprio 0
	s_waitcnt vmcnt(8)
	s_waitcnt lgkmcnt(0)
	s_barrier
	s_waitcnt lgkmcnt(0)
	v_mfma_f32_16x16x32_bf16 v[124:127], v[128:131], v[186:189], v[124:127]
	v_mfma_f32_16x16x32_bf16 v[124:127], v[132:135], v[190:193], v[124:127]
	v_mfma_f32_16x16x32_bf16 v[120:123], v[140:143], v[190:193], v[120:123]
	v_mfma_f32_16x16x32_bf16 v[120:123], v[136:139], v[186:189], v[120:123]
	v_mfma_f32_16x16x32_bf16 v[116:119], v[144:147], v[186:189], v[116:119]
	v_mfma_f32_16x16x32_bf16 v[116:119], v[148:151], v[190:193], v[116:119]
	v_mfma_f32_16x16x32_bf16 v[112:115], v[182:185], v[190:193], v[112:115]
	v_mfma_f32_16x16x32_bf16 v[112:115], v[170:173], v[186:189], v[112:115]
	v_mfma_f32_16x16x32_bf16 v[96:99], v[170:173], v[194:197], v[96:99]
	v_mfma_f32_16x16x32_bf16 v[96:99], v[182:185], v[198:201], v[96:99]
	v_mfma_f32_16x16x32_bf16 v[100:103], v[148:151], v[198:201], v[100:103]
	v_mfma_f32_16x16x32_bf16 v[100:103], v[144:147], v[194:197], v[100:103]
	v_mfma_f32_16x16x32_bf16 v[104:107], v[136:139], v[194:197], v[104:107]
	v_mfma_f32_16x16x32_bf16 v[104:107], v[140:143], v[198:201], v[104:107]
	v_mfma_f32_16x16x32_bf16 v[108:111], v[132:135], v[198:201], v[108:111]
	v_mfma_f32_16x16x32_bf16 v[108:111], v[128:131], v[194:197], v[108:111]
	v_mfma_f32_16x16x32_bf16 v[92:95], v[128:131], v[202:205], v[92:95]
	v_mfma_f32_16x16x32_bf16 v[92:95], v[132:135], v[206:209], v[92:95]
	v_mfma_f32_16x16x32_bf16 v[88:91], v[140:143], v[206:209], v[88:91]
	v_mfma_f32_16x16x32_bf16 v[88:91], v[136:139], v[202:205], v[88:91]
	v_mfma_f32_16x16x32_bf16 v[84:87], v[144:147], v[202:205], v[84:87]
	v_mfma_f32_16x16x32_bf16 v[84:87], v[148:151], v[206:209], v[84:87]
	v_mfma_f32_16x16x32_bf16 v[80:83], v[182:185], v[206:209], v[80:83]
	v_mfma_f32_16x16x32_bf16 v[80:83], v[170:173], v[202:205], v[80:83]
	v_mfma_f32_16x16x32_bf16 v[64:67], v[170:173], v[210:213], v[64:67]
	v_mfma_f32_16x16x32_bf16 v[64:67], v[182:185], v[214:217], v[64:67]
	v_mfma_f32_16x16x32_bf16 v[68:71], v[148:151], v[214:217], v[68:71]
	v_mfma_f32_16x16x32_bf16 v[68:71], v[144:147], v[210:213], v[68:71]
	v_mfma_f32_16x16x32_bf16 v[72:75], v[136:139], v[210:213], v[72:75]
	v_mfma_f32_16x16x32_bf16 v[72:75], v[140:143], v[214:217], v[72:75]
	v_mfma_f32_16x16x32_bf16 v[76:79], v[132:135], v[214:217], v[76:79]
	v_mfma_f32_16x16x32_bf16 v[76:79], v[128:131], v[210:213], v[76:79]
	s_barrier
	s_setprio 1
	s_add_i32 s58, s48, s37
	v_lshl_add_u64 v[218:219], s[24:25], 0, v[154:155]
	s_mov_b32 m0, s58
	v_lshl_add_u64 v[220:221], s[24:25], 0, v[158:159]
	global_load_lds_dwordx4 v[218:219], off
	s_add_i32 m0, s58, 0x2000
	s_add_u32 s58, s24, 0x400000
	s_addc_u32 s59, s25, 0
	s_add_i32 s60, s49, s37
	global_load_lds_dwordx4 v[220:221], off
	v_lshl_add_u64 v[186:187], s[58:59], 0, v[154:155]
	s_mov_b32 m0, s60
	v_lshl_add_u64 v[222:223], s[26:27], 0, v[152:153]
	global_load_lds_dwordx4 v[186:187], off
	v_lshl_add_u64 v[186:187], s[58:59], 0, v[158:159]
	s_add_i32 m0, s60, 0x2000
	v_lshl_add_u64 v[224:225], s[26:27], 0, v[156:157]
	global_load_lds_dwordx4 v[186:187], off
	s_mov_b32 m0, s38
	s_nop 0
	global_load_lds_dwordx4 v[222:223], off
	s_mov_b32 m0, s39
	s_nop 0
	global_load_lds_dwordx4 v[224:225], off
	ds_read_b128 v[186:189], v179 offset:16384
	ds_read_b128 v[190:193], v179 offset:17408
	ds_read_b128 v[194:197], v179 offset:18432
	ds_read_b128 v[198:201], v179 offset:19456
	ds_read_b128 v[202:205], v179 offset:20480
	ds_read_b128 v[206:209], v179 offset:21504
	ds_read_b128 v[210:213], v179 offset:22528
	ds_read_b128 v[214:217], v179 offset:23552
	s_setprio 0
	s_waitcnt vmcnt(8)
	s_waitcnt lgkmcnt(0)
	s_barrier
	s_waitcnt lgkmcnt(0)
	v_mfma_f32_16x16x32_bf16 v[60:63], v[128:131], v[186:189], v[60:63]
	v_mfma_f32_16x16x32_bf16 v[60:63], v[132:135], v[190:193], v[60:63]
	v_mfma_f32_16x16x32_bf16 v[56:59], v[140:143], v[190:193], v[56:59]
	v_mfma_f32_16x16x32_bf16 v[56:59], v[136:139], v[186:189], v[56:59]
	v_mfma_f32_16x16x32_bf16 v[52:55], v[144:147], v[186:189], v[52:55]
	v_mfma_f32_16x16x32_bf16 v[52:55], v[148:151], v[190:193], v[52:55]
	v_mfma_f32_16x16x32_bf16 v[48:51], v[182:185], v[190:193], v[48:51]
	v_mfma_f32_16x16x32_bf16 v[48:51], v[170:173], v[186:189], v[48:51]
	v_mfma_f32_16x16x32_bf16 v[32:35], v[170:173], v[194:197], v[32:35]
	v_mfma_f32_16x16x32_bf16 v[32:35], v[182:185], v[198:201], v[32:35]
	v_mfma_f32_16x16x32_bf16 v[36:39], v[148:151], v[198:201], v[36:39]
	v_mfma_f32_16x16x32_bf16 v[36:39], v[144:147], v[194:197], v[36:39]
	v_mfma_f32_16x16x32_bf16 v[40:43], v[136:139], v[194:197], v[40:43]
	v_mfma_f32_16x16x32_bf16 v[40:43], v[140:143], v[198:201], v[40:43]
	v_mfma_f32_16x16x32_bf16 v[44:47], v[132:135], v[198:201], v[44:47]
	v_mfma_f32_16x16x32_bf16 v[44:47], v[128:131], v[194:197], v[44:47]
	v_mfma_f32_16x16x32_bf16 v[28:31], v[128:131], v[202:205], v[28:31]
	v_mfma_f32_16x16x32_bf16 v[28:31], v[132:135], v[206:209], v[28:31]
	v_mfma_f32_16x16x32_bf16 v[24:27], v[140:143], v[206:209], v[24:27]
	v_mfma_f32_16x16x32_bf16 v[24:27], v[136:139], v[202:205], v[24:27]
	v_mfma_f32_16x16x32_bf16 v[20:23], v[144:147], v[202:205], v[20:23]
	v_mfma_f32_16x16x32_bf16 v[20:23], v[148:151], v[206:209], v[20:23]
	v_mfma_f32_16x16x32_bf16 v[16:19], v[182:185], v[206:209], v[16:19]
	v_mfma_f32_16x16x32_bf16 v[16:19], v[170:173], v[202:205], v[16:19]
	v_mfma_f32_16x16x32_bf16 v[0:3], v[170:173], v[210:213], v[0:3]
	v_mfma_f32_16x16x32_bf16 v[0:3], v[182:185], v[214:217], v[0:3]
	v_mfma_f32_16x16x32_bf16 v[4:7], v[148:151], v[214:217], v[4:7]
	v_mfma_f32_16x16x32_bf16 v[4:7], v[144:147], v[210:213], v[4:7]
	v_mfma_f32_16x16x32_bf16 v[8:11], v[136:139], v[210:213], v[8:11]
	v_mfma_f32_16x16x32_bf16 v[8:11], v[140:143], v[214:217], v[8:11]
	v_mfma_f32_16x16x32_bf16 v[12:15], v[132:135], v[214:217], v[12:15]
	v_mfma_f32_16x16x32_bf16 v[12:15], v[128:131], v[210:213], v[12:15]
	s_barrier
	s_setprio 1
	s_add_i32 s58, 0, 0x18000
	s_add_i32 s59, 0, 0x1c000
	v_add_u32_e32 v140, s58, v174
	v_add_u32_e32 v181, s59, v174
	ds_read_b128 v[128:131], v140
	ds_read_b128 v[132:135], v140 offset:1024
	ds_read_b128 v[136:139], v140 offset:2048
	ds_read_b128 v[140:143], v140 offset:3072
	ds_read_b128 v[144:147], v181
	ds_read_b128 v[148:151], v181 offset:1024
	ds_read_b128 v[170:173], v181 offset:2048
	ds_read_b128 v[182:185], v181 offset:3072
	s_add_u32 s26, s26, 0x400000
	s_addc_u32 s27, s27, 0
	s_mov_b32 m0, s40
	v_lshl_add_u64 v[186:187], s[26:27], 0, v[152:153]
	global_load_lds_dwordx4 v[186:187], off
	v_lshl_add_u64 v[186:187], s[26:27], 0, v[156:157]
	s_mov_b32 m0, s41
	s_nop 0
	global_load_lds_dwordx4 v[186:187], off
	ds_read_b128 v[186:189], v179 offset:32768
	ds_read_b128 v[190:193], v179 offset:33792
	ds_read_b128 v[194:197], v179 offset:34816
	ds_read_b128 v[198:201], v179 offset:35840
	ds_read_b128 v[202:205], v179 offset:36864
	ds_read_b128 v[206:209], v179 offset:37888
	ds_read_b128 v[210:213], v179 offset:38912
	ds_read_b128 v[214:217], v179 offset:39936
	s_setprio 0
	s_waitcnt vmcnt(8)
	s_waitcnt lgkmcnt(0)
	s_barrier
	s_waitcnt lgkmcnt(0)
	v_mfma_f32_16x16x32_bf16 v[124:127], v[128:131], v[186:189], v[124:127]
	v_mfma_f32_16x16x32_bf16 v[124:127], v[132:135], v[190:193], v[124:127]
	v_mfma_f32_16x16x32_bf16 v[120:123], v[140:143], v[190:193], v[120:123]
	v_mfma_f32_16x16x32_bf16 v[120:123], v[136:139], v[186:189], v[120:123]
	v_mfma_f32_16x16x32_bf16 v[116:119], v[144:147], v[186:189], v[116:119]
	v_mfma_f32_16x16x32_bf16 v[116:119], v[148:151], v[190:193], v[116:119]
	v_mfma_f32_16x16x32_bf16 v[112:115], v[182:185], v[190:193], v[112:115]
	v_mfma_f32_16x16x32_bf16 v[112:115], v[170:173], v[186:189], v[112:115]
	v_mfma_f32_16x16x32_bf16 v[96:99], v[170:173], v[194:197], v[96:99]
	v_mfma_f32_16x16x32_bf16 v[96:99], v[182:185], v[198:201], v[96:99]
	v_mfma_f32_16x16x32_bf16 v[100:103], v[148:151], v[198:201], v[100:103]
	v_mfma_f32_16x16x32_bf16 v[100:103], v[144:147], v[194:197], v[100:103]
	v_mfma_f32_16x16x32_bf16 v[104:107], v[136:139], v[194:197], v[104:107]
	v_mfma_f32_16x16x32_bf16 v[104:107], v[140:143], v[198:201], v[104:107]
	v_mfma_f32_16x16x32_bf16 v[108:111], v[132:135], v[198:201], v[108:111]
	v_mfma_f32_16x16x32_bf16 v[108:111], v[128:131], v[194:197], v[108:111]
	v_mfma_f32_16x16x32_bf16 v[92:95], v[128:131], v[202:205], v[92:95]
	v_mfma_f32_16x16x32_bf16 v[92:95], v[132:135], v[206:209], v[92:95]
	v_mfma_f32_16x16x32_bf16 v[88:91], v[140:143], v[206:209], v[88:91]
	v_mfma_f32_16x16x32_bf16 v[88:91], v[136:139], v[202:205], v[88:91]
	v_mfma_f32_16x16x32_bf16 v[84:87], v[144:147], v[202:205], v[84:87]
	v_mfma_f32_16x16x32_bf16 v[84:87], v[148:151], v[206:209], v[84:87]
	v_mfma_f32_16x16x32_bf16 v[80:83], v[182:185], v[206:209], v[80:83]
	v_mfma_f32_16x16x32_bf16 v[80:83], v[170:173], v[202:205], v[80:83]
	v_mfma_f32_16x16x32_bf16 v[64:67], v[170:173], v[210:213], v[64:67]
	v_mfma_f32_16x16x32_bf16 v[64:67], v[182:185], v[214:217], v[64:67]
	v_mfma_f32_16x16x32_bf16 v[68:71], v[148:151], v[214:217], v[68:71]
	v_mfma_f32_16x16x32_bf16 v[68:71], v[144:147], v[210:213], v[68:71]
	v_mfma_f32_16x16x32_bf16 v[72:75], v[136:139], v[210:213], v[72:75]
	v_mfma_f32_16x16x32_bf16 v[72:75], v[140:143], v[214:217], v[72:75]
	v_mfma_f32_16x16x32_bf16 v[76:79], v[132:135], v[214:217], v[76:79]
	v_mfma_f32_16x16x32_bf16 v[76:79], v[128:131], v[210:213], v[76:79]
	s_barrier
	s_setprio 1
	s_add_i32 s26, s58, s37
	v_lshl_add_u64 v[186:187], v[218:219], 0, s[14:15]
	s_mov_b32 m0, s26
	s_nop 0
	global_load_lds_dwordx4 v[186:187], off
	s_add_i32 m0, s26, 0x2000
	s_add_u32 s24, s24, 0x400800
	v_lshl_add_u64 v[186:187], v[220:221], 0, s[14:15]
	s_addc_u32 s25, s25, 0
	s_add_i32 s26, s59, s37
	global_load_lds_dwordx4 v[186:187], off
	v_lshl_add_u64 v[186:187], s[24:25], 0, v[154:155]
	s_mov_b32 m0, s26
	s_nop 0
	global_load_lds_dwordx4 v[186:187], off
	v_lshl_add_u64 v[186:187], s[24:25], 0, v[158:159]
	s_add_i32 m0, s26, 0x2000
	s_nop 0
	global_load_lds_dwordx4 v[186:187], off
	v_lshl_add_u64 v[186:187], v[222:223], 0, s[14:15]
	s_mov_b32 m0, s43
	s_nop 0
	global_load_lds_dwordx4 v[186:187], off
	v_lshl_add_u64 v[186:187], v[224:225], 0, s[14:15]
	s_mov_b32 m0, s44
	s_nop 0
	global_load_lds_dwordx4 v[186:187], off
	ds_read_b128 v[186:189], v179 offset:49152
	ds_read_b128 v[190:193], v179 offset:50176
	ds_read_b128 v[194:197], v179 offset:51200
	ds_read_b128 v[198:201], v179 offset:52224
	ds_read_b128 v[202:205], v179 offset:53248
	ds_read_b128 v[206:209], v179 offset:54272
	ds_read_b128 v[210:213], v179 offset:55296
	ds_read_b128 v[214:217], v179 offset:56320
	s_setprio 0
	s_waitcnt vmcnt(8)
	s_waitcnt lgkmcnt(0)
	s_barrier
	s_waitcnt lgkmcnt(0)
	v_mfma_f32_16x16x32_bf16 v[60:63], v[128:131], v[186:189], v[60:63]
	v_mfma_f32_16x16x32_bf16 v[60:63], v[132:135], v[190:193], v[60:63]
	v_mfma_f32_16x16x32_bf16 v[56:59], v[140:143], v[190:193], v[56:59]
	v_mfma_f32_16x16x32_bf16 v[56:59], v[136:139], v[186:189], v[56:59]
	v_mfma_f32_16x16x32_bf16 v[52:55], v[144:147], v[186:189], v[52:55]
	v_mfma_f32_16x16x32_bf16 v[52:55], v[148:151], v[190:193], v[52:55]
	v_mfma_f32_16x16x32_bf16 v[48:51], v[182:185], v[190:193], v[48:51]
	v_mfma_f32_16x16x32_bf16 v[48:51], v[170:173], v[186:189], v[48:51]
	v_mfma_f32_16x16x32_bf16 v[32:35], v[170:173], v[194:197], v[32:35]
	v_mfma_f32_16x16x32_bf16 v[32:35], v[182:185], v[198:201], v[32:35]
	v_mfma_f32_16x16x32_bf16 v[36:39], v[148:151], v[198:201], v[36:39]
	v_mfma_f32_16x16x32_bf16 v[36:39], v[144:147], v[194:197], v[36:39]
	v_mfma_f32_16x16x32_bf16 v[40:43], v[136:139], v[194:197], v[40:43]
	v_mfma_f32_16x16x32_bf16 v[40:43], v[140:143], v[198:201], v[40:43]
	v_mfma_f32_16x16x32_bf16 v[44:47], v[132:135], v[198:201], v[44:47]
	v_mfma_f32_16x16x32_bf16 v[44:47], v[128:131], v[194:197], v[44:47]
	v_mfma_f32_16x16x32_bf16 v[28:31], v[128:131], v[202:205], v[28:31]
	v_mfma_f32_16x16x32_bf16 v[28:31], v[132:135], v[206:209], v[28:31]
	v_mfma_f32_16x16x32_bf16 v[24:27], v[140:143], v[206:209], v[24:27]
	v_mfma_f32_16x16x32_bf16 v[24:27], v[136:139], v[202:205], v[24:27]
	v_mfma_f32_16x16x32_bf16 v[20:23], v[144:147], v[202:205], v[20:23]
	v_mfma_f32_16x16x32_bf16 v[20:23], v[148:151], v[206:209], v[20:23]
	v_mfma_f32_16x16x32_bf16 v[16:19], v[182:185], v[206:209], v[16:19]
	v_mfma_f32_16x16x32_bf16 v[16:19], v[170:173], v[202:205], v[16:19]
	v_mfma_f32_16x16x32_bf16 v[0:3], v[170:173], v[210:213], v[0:3]
	v_mfma_f32_16x16x32_bf16 v[0:3], v[182:185], v[214:217], v[0:3]
	v_mfma_f32_16x16x32_bf16 v[4:7], v[148:151], v[214:217], v[4:7]
	v_mfma_f32_16x16x32_bf16 v[4:7], v[144:147], v[210:213], v[4:7]
	v_mfma_f32_16x16x32_bf16 v[8:11], v[136:139], v[210:213], v[8:11]
	v_mfma_f32_16x16x32_bf16 v[8:11], v[140:143], v[214:217], v[8:11]
	v_mfma_f32_16x16x32_bf16 v[12:15], v[132:135], v[214:217], v[12:15]
	v_mfma_f32_16x16x32_bf16 v[12:15], v[128:131], v[210:213], v[12:15]
	s_barrier
	s_setprio 1
	s_add_i32 s57, s57, 2
	s_add_u32 s22, s22, 0x1000
	s_addc_u32 s23, s23, 0
	s_add_u32 s55, s55, 0x1000
	s_addc_u32 s56, s56, 0
	s_cmpk_gt_u32 s57, 0xfd
	s_cbranch_scc0 .LBB0_1625
	s_setprio 0
	s_and_b64 vcc, exec, s[6:7]
	s_cbranch_vccz .LBB0_1628
	s_barrier
